# v114 + attention P.V section software-pipelined one step: V^T fragment reads of step k+1 issued before the wait of step k (alternate VGPR quad), waits lgkmcnt(2) instead of lgkmcnt(0)
# speedup vs baseline: 1.0101x; 1.0015x over previous
; #define LAS __attribute__((address_space(3)))
; __device__ __forceinline__ s16x4 vtr(const LAS unsigned char* p) { return __builtin_bit_cast(s16x4, __builtin_amdgcn_ds_read_tr16_b64_v4i16((LAS v4i16_t*)p)); }
; template <bool SAMPLE> ...
;     ...
;     u32x4 pw[5][2];
; #pragma unroll
;     for (int t = 0; t < 5; ++t) {
; #pragma unroll
;         for (int i = 0; i < 16; ++i) { p[t][i] = __builtin_amdgcn_exp2f(p[t][i] - mx); lsum += p[t][i]; }
; #pragma unroll
;         for (int s = 0; s < 2; ++s) { pw[t][s].x = pk_bf16(p[t][8 * s + 0], p[t][8 * s + 1]); pw[t][s].y = pk_bf16(p[t][8 * s + 2], p[t][8 * s + 3]); pw[t][s].z = pk_bf16(p[t][8 * s + 4], p[t][8 * s + 5]); pw[t][s].w = pk_bf16(p[t][8 * s + 6], p[t][8 * s + 7]); }
;     }
;     lsum += __shfl_xor(lsum, 32);
;     const float denom = lsum + __builtin_amdgcn_exp2f(sk - mx);
;     if (hi == 0) wsf[r32] = 1.0f / denom;
;     __builtin_amdgcn_sched_barrier(0);
;     f32x16 o[2];
; #pragma unroll
;     for (int d0 = 0; d0 < 2; ++d0)
; #pragma unroll
;         for (int i = 0; i < 16; ++i) o[d0][i] = 0.f;
;     const int i16 = lane & 15;
;     const LAS unsigned char* vb = Vl + (4 * hi + (i16 >> 2)) * 64 + ((lane >> 4) & 1) * 32 + (i16 & 3) * 8;
; #pragma unroll
;     for (int t = 0; t < 5; ++t)
; #pragma unroll
;         for (int s = 0; s < 2; ++s) {
;             const bf16x8 pa = __builtin_bit_cast(bf16x8, pw[t][s]);
; #pragma unroll
;             for (int d0 = 0; d0 < 2; ++d0) {
;                 const s16x4 vlo = vtr(vb + d0 * vhalf + (32 * t + 16 * s) * 64), vhi = vtr(vb + d0 * vhalf + (32 * t + 16 * s + 8) * 64);
;                 const bf16x8 vf = (bf16x8){vlo[0], vlo[1], vlo[2], vlo[3], vhi[0], vhi[1], vhi[2], vhi[3]};
;                 o[d0] = __builtin_amdgcn_mfma_f32_32x32x16_bf16(pa, vf, o[d0], 0, 0, 0);
;             }
;         }
.LBB0_458:
	s_or_b64 exec, exec, s[4:5]
	v_ashrrev_i32_e32 v127, 31, v126
	v_cvt_pk_bf16_f32 v32, v32, v33
	v_cvt_pk_bf16_f32 v33, v34, v35
	v_cvt_pk_bf16_f32 v34, v51, v50
	v_cvt_pk_bf16_f32 v35, v49, v48
	v_cvt_pk_bf16_f32 v36, v36, v37
	v_cvt_pk_bf16_f32 v37, v38, v39
	v_cvt_pk_bf16_f32 v38, v83, v82
	v_cvt_pk_bf16_f32 v39, v81, v80
	v_cvt_pk_bf16_f32 v40, v40, v41
	v_cvt_pk_bf16_f32 v41, v42, v43
	v_cvt_pk_bf16_f32 v42, v44, v45
	v_cvt_pk_bf16_f32 v43, v46, v47
	v_cvt_pk_bf16_f32 v44, v96, v97
	v_cvt_pk_bf16_f32 v45, v98, v99
	v_cvt_pk_bf16_f32 v46, v100, v101
	v_cvt_pk_bf16_f32 v47, v102, v103
	v_cvt_pk_bf16_f32 v48, v24, v25
	v_cvt_pk_bf16_f32 v49, v26, v27
	v_cvt_pk_bf16_f32 v50, v28, v29
	v_cvt_pk_bf16_f32 v51, v30, v31
	v_cvt_pk_bf16_f32 v52, v16, v17
	s_waitcnt lgkmcnt(0)
	v_cvt_pk_bf16_f32 v53, v18, v19
	v_cvt_pk_bf16_f32 v54, v20, v21
	v_cvt_pk_bf16_f32 v55, v22, v23
	v_cvt_pk_bf16_f32 v80, v8, v9
	v_cvt_pk_bf16_f32 v81, v10, v11
	v_cvt_pk_bf16_f32 v82, v12, v13
	v_cvt_pk_bf16_f32 v83, v14, v15
	v_cvt_pk_bf16_f32 v84, v0, v1
	v_cvt_pk_bf16_f32 v85, v2, v3
	v_cvt_pk_bf16_f32 v86, v4, v5
	v_cvt_pk_bf16_f32 v87, v6, v7
	v_cvt_pk_bf16_f32 v88, v88, v89
	v_cvt_pk_bf16_f32 v89, v90, v91
	v_cvt_pk_bf16_f32 v90, v92, v93
	v_cvt_pk_bf16_f32 v91, v94, v95
	v_cvt_pk_bf16_f32 v16, v56, v57
	v_cvt_pk_bf16_f32 v17, v58, v59
	v_cvt_pk_bf16_f32 v18, v60, v61
	v_cvt_pk_bf16_f32 v19, v62, v63
	v_add_u32_e32 v0, s70, v115
	v_add3_u32 v60, v0, v117, v118
	ds_read_b64_tr_b16 v[0:1], v60 offset:36864
	ds_read_b64_tr_b16 v[2:3], v60 offset:37376
	ds_read_b64_tr_b16 v[20:21], v60 offset:53248
	ds_read_b64_tr_b16 v[22:23], v60 offset:53760
	s_waitcnt lgkmcnt(2)
	v_mfma_f32_32x32x16_bf16 v[0:15], v[16:19], v[0:3], 0
	ds_read_b64_tr_b16 v[56:57], v60 offset:37888
	ds_read_b64_tr_b16 v[58:59], v60 offset:38400
	s_waitcnt lgkmcnt(2)
	v_mfma_f32_32x32x16_bf16 v[16:31], v[16:19], v[20:23], 0
	ds_read_b64_tr_b16 v[236:237], v60 offset:54272
	ds_read_b64_tr_b16 v[238:239], v60 offset:54784
	s_waitcnt lgkmcnt(2)
	v_mfma_f32_32x32x16_bf16 v[0:15], v[88:91], v[56:59], v[0:15]
	ds_read_b64_tr_b16 v[56:57], v60 offset:38912
	ds_read_b64_tr_b16 v[58:59], v60 offset:39424
	s_waitcnt lgkmcnt(2)
	v_mfma_f32_32x32x16_bf16 v[16:31], v[88:91], v[236:239], v[16:31]
	ds_read_b64_tr_b16 v[236:237], v60 offset:55296
	ds_read_b64_tr_b16 v[238:239], v60 offset:55808
	s_waitcnt lgkmcnt(2)
	v_mfma_f32_32x32x16_bf16 v[0:15], v[84:87], v[56:59], v[0:15]
	ds_read_b64_tr_b16 v[56:57], v60 offset:39936
	ds_read_b64_tr_b16 v[58:59], v60 offset:40448
	s_waitcnt lgkmcnt(2)
	v_mfma_f32_32x32x16_bf16 v[16:31], v[84:87], v[236:239], v[16:31]
	ds_read_b64_tr_b16 v[236:237], v60 offset:56320
	ds_read_b64_tr_b16 v[238:239], v60 offset:56832
	s_waitcnt lgkmcnt(2)
	v_mfma_f32_32x32x16_bf16 v[0:15], v[80:83], v[56:59], v[0:15]
	ds_read_b64_tr_b16 v[56:57], v60 offset:40960
	ds_read_b64_tr_b16 v[58:59], v60 offset:41472
	s_waitcnt lgkmcnt(2)
	v_mfma_f32_32x32x16_bf16 v[16:31], v[80:83], v[236:239], v[16:31]
	ds_read_b64_tr_b16 v[236:237], v60 offset:57344
	ds_read_b64_tr_b16 v[238:239], v60 offset:57856
	s_waitcnt lgkmcnt(2)
	v_mfma_f32_32x32x16_bf16 v[0:15], v[52:55], v[56:59], v[0:15]
	ds_read_b64_tr_b16 v[56:57], v60 offset:41984
	ds_read_b64_tr_b16 v[58:59], v60 offset:42496
	s_waitcnt lgkmcnt(2)
	v_mfma_f32_32x32x16_bf16 v[16:31], v[52:55], v[236:239], v[16:31]
	ds_read_b64_tr_b16 v[236:237], v60 offset:58368
	ds_read_b64_tr_b16 v[238:239], v60 offset:58880
	s_waitcnt lgkmcnt(2)
	v_mfma_f32_32x32x16_bf16 v[0:15], v[48:51], v[56:59], v[0:15]
	ds_read_b64_tr_b16 v[56:57], v60 offset:43008
	ds_read_b64_tr_b16 v[58:59], v60 offset:43520
	s_waitcnt lgkmcnt(2)
	v_mfma_f32_32x32x16_bf16 v[16:31], v[48:51], v[236:239], v[16:31]
	ds_read_b64_tr_b16 v[236:237], v60 offset:59392
	ds_read_b64_tr_b16 v[238:239], v60 offset:59904
	s_waitcnt lgkmcnt(2)
	v_mfma_f32_32x32x16_bf16 v[0:15], v[44:47], v[56:59], v[0:15]
	ds_read_b64_tr_b16 v[56:57], v60 offset:44032
	ds_read_b64_tr_b16 v[58:59], v60 offset:44544
	s_waitcnt lgkmcnt(2)
	v_mfma_f32_32x32x16_bf16 v[16:31], v[44:47], v[236:239], v[16:31]
	ds_read_b64_tr_b16 v[236:237], v60 offset:60416
	ds_read_b64_tr_b16 v[238:239], v60 offset:60928
	s_waitcnt lgkmcnt(2)
	v_mfma_f32_32x32x16_bf16 v[0:15], v[40:43], v[56:59], v[0:15]
	ds_read_b64_tr_b16 v[56:57], v60 offset:45056
	ds_read_b64_tr_b16 v[58:59], v60 offset:45568
	s_waitcnt lgkmcnt(2)
	v_mfma_f32_32x32x16_bf16 v[16:31], v[40:43], v[236:239], v[16:31]
	ds_read_b64_tr_b16 v[236:237], v60 offset:61440
	ds_read_b64_tr_b16 v[238:239], v60 offset:61952
	s_waitcnt lgkmcnt(2)
	v_mfma_f32_32x32x16_bf16 v[0:15], v[36:39], v[56:59], v[0:15]
	ds_read_b64_tr_b16 v[56:57], v60 offset:46080
	ds_read_b64_tr_b16 v[58:59], v60 offset:46592
	s_waitcnt lgkmcnt(2)
	v_mfma_f32_32x32x16_bf16 v[16:31], v[36:39], v[236:239], v[16:31]
	ds_read_b64_tr_b16 v[236:237], v60 offset:62464
	ds_read_b64_tr_b16 v[238:239], v60 offset:62976
	s_waitcnt lgkmcnt(2)
	v_mfma_f32_32x32x16_bf16 v[0:15], v[32:35], v[56:59], v[0:15]
	s_waitcnt lgkmcnt(0)
	v_mfma_f32_32x32x16_bf16 v[16:31], v[32:35], v[236:239], v[16:31]
	s_waitcnt lgkmcnt(0)
	ds_read_b128 v[32:35], v112
	ds_read_b128 v[36:39], v112 offset:32
	v_mov_b32_e32 v125, v173
	s_add_i32 s71, s71, s42
	s_cmpk_gt_i32 s71, 0xff
	s_waitcnt lgkmcnt(1)
; #define LAS __attribute__((address_space(3)))
; __device__ __forceinline__ u32x4 pack8(const float (&f)[8]) { u32x4 w; w.x = pk_bf16(f[0], f[1]); w.y = pk_bf16(f[2], f[3]); w.z = pk_bf16(f[4], f[5]); w.w = pk_bf16(f[6], f[7]); return w; }
; __device__ __forceinline__ int crow(int r, int hi) { return (r & 3) + 8 * (r >> 2) + 4 * hi; }
; template <bool SAMPLE> ...
;     ...
;     asm volatile("s_waitcnt lgkmcnt(0)" ::: "memory");
; #pragma unroll
;     for (int i = 0; i < 16; ++i) {
;         const int qq = crow(i, hi);
;         const float rl = wsf[qq];
; #pragma unroll
;         for (int d0 = 0; d0 < 2; ++d0) ost[qq * 64 + d0 * 32 + r32] = (bf16_t)(pk_bf16(o[d0][i] * rl, 0.f) & 0xffffu);
;     }
;     asm volatile("s_waitcnt lgkmcnt(0)" ::: "memory");
; #pragma unroll
;     for (int it4 = 0; it4 < 4; ++it4) {
;         const int qq = it4 * 8 + (lane >> 3), ch = lane & 7;
;         const int orow = SAMPLE ? row0 + (qq & 7) : row0 + qq;
;         const int ohead = SAMPLE ? head0 + (qq >> 3) : head0;
;         const u32x4 ow = *(const LAS u32x4*)(ost + qq * 64 + ch * 8);
;         float of[8], zf[8], yv[8];
;         unpack8(ow, of); unpack8(zw[it4], zf);
; #pragma unroll
;         for (int k = 0; k < 8; ++k) yv[k] = of[k] * zf[k];
;         *(u32x4*)(Y + (size_t)orow * D + 512 + ohead * 64 + ch * 8) = pack8(yv);
;     }
	s_nop 1
	v_mul_f32_e32 v0, v0, v32
	s_nop 2
	v_mul_f32_e32 v16, v16, v32
	v_cvt_pk_bf16_f32 v0, v0, s0
	v_cvt_pk_bf16_f32 v16, v16, s0
	ds_write_b16 v116, v0
	ds_write_b16 v116, v16 offset:64
	v_mul_f32_e32 v0, v1, v33
	v_cvt_pk_bf16_f32 v0, v0, s0
	ds_write_b16 v119, v0
	v_mul_f32_e32 v0, v17, v33
	v_cvt_pk_bf16_f32 v0, v0, s0
	ds_write_b16 v119, v0 offset:64
	v_mul_f32_e32 v0, v2, v34
	v_cvt_pk_bf16_f32 v0, v0, s0
	ds_write_b16 v120, v0
	v_mul_f32_e32 v0, v18, v34
	v_cvt_pk_bf16_f32 v0, v0, s0
	ds_write_b16 v120, v0 offset:64
	v_mul_f32_e32 v0, v3, v35
	v_cvt_pk_bf16_f32 v0, v0, s0
	ds_write_b16 v121, v0
	v_mul_f32_e32 v0, v19, v35
	v_cvt_pk_bf16_f32 v0, v0, s0
	ds_write_b16 v121, v0 offset:64
	s_waitcnt lgkmcnt(8)
	v_mul_f32_e32 v0, v4, v36
	v_cvt_pk_bf16_f32 v0, v0, s0
	ds_write_b16 v122, v0
	v_mul_f32_e32 v0, v20, v36
	v_cvt_pk_bf16_f32 v0, v0, s0
	ds_write_b16 v122, v0 offset:64
	v_mul_f32_e32 v0, v5, v37
	v_cvt_pk_bf16_f32 v0, v0, s0
	ds_write_b16 v123, v0
	v_mul_f32_e32 v0, v21, v37
	v_cvt_pk_bf16_f32 v0, v0, s0
	ds_write_b16 v123, v0 offset:64
	v_mul_f32_e32 v0, v6, v38
	v_cvt_pk_bf16_f32 v0, v0, s0
	ds_write_b16 v135, v0
	v_mul_f32_e32 v0, v22, v38
	v_cvt_pk_bf16_f32 v0, v0, s0
	ds_write_b16 v135, v0 offset:64
	v_mul_f32_e32 v0, v7, v39
	v_cvt_pk_bf16_f32 v0, v0, s0
	ds_write_b16 v134, v0
	ds_read_b128 v[0:3], v112 offset:64
	v_mul_f32_e32 v4, v23, v39
	v_cvt_pk_bf16_f32 v4, v4, s0
	ds_write_b16 v134, v4 offset:64
	ds_read_b128 v[4:7], v112 offset:96
	s_waitcnt lgkmcnt(2)
	v_mul_f32_e32 v8, v8, v0
	v_mul_f32_e32 v0, v24, v0
	v_cvt_pk_bf16_f32 v0, v0, s0
	ds_write_b16 v136, v0 offset:64
	v_mul_f32_e32 v0, v9, v1
	v_cvt_pk_bf16_f32 v0, v0, s0
	ds_write_b16 v137, v0
	v_mul_f32_e32 v0, v25, v1
	v_cvt_pk_bf16_f32 v0, v0, s0
	ds_write_b16 v137, v0 offset:64
	v_mul_f32_e32 v0, v10, v2
	v_cvt_pk_bf16_f32 v0, v0, s0
	ds_write_b16 v138, v0
	v_mul_f32_e32 v0, v26, v2
	v_cvt_pk_bf16_f32 v0, v0, s0
	ds_write_b16 v138, v0 offset:64
	v_mul_f32_e32 v0, v11, v3
	v_cvt_pk_bf16_f32 v0, v0, s0
	ds_write_b16 v139, v0
	v_mul_f32_e32 v0, v27, v3
	v_cvt_pk_bf16_f32 v0, v0, s0
	ds_write_b16 v139, v0 offset:64
	s_waitcnt lgkmcnt(7)
	v_mul_f32_e32 v0, v12, v4
	v_cvt_pk_bf16_f32 v0, v0, s0
	ds_write_b16 v140, v0
	v_mul_f32_e32 v0, v28, v4
	v_cvt_pk_bf16_f32 v0, v0, s0
	ds_write_b16 v140, v0 offset:64
	v_mul_f32_e32 v0, v13, v5
	v_cvt_pk_bf16_f32 v0, v0, s0
	ds_write_b16 v141, v0
	v_mul_f32_e32 v0, v29, v5
	v_cvt_pk_bf16_f32 v0, v0, s0
	ds_write_b16 v141, v0 offset:64
	v_mul_f32_e32 v0, v14, v6
	v_cvt_pk_bf16_f32 v0, v0, s0
	ds_write_b16 v142, v0
	v_mul_f32_e32 v0, v30, v6
	v_cvt_pk_bf16_f32 v0, v0, s0
	ds_write_b16 v142, v0 offset:64
	v_mul_f32_e32 v0, v15, v7
	v_cvt_pk_bf16_f32 v0, v0, s0
	ds_write_b16 v143, v0
	v_mul_f32_e32 v0, v31, v7
	v_cvt_pk_bf16_f32 v8, v8, s0
	v_cvt_pk_bf16_f32 v0, v0, s0
	ds_write_b16 v136, v8
	ds_write_b16 v143, v0 offset:64
	s_waitcnt lgkmcnt(0)
	ds_read_b128 v[0:3], v144
	ds_read_b128 v[4:7], v145
	v_lshlrev_b32_e32 v10, 16, v76
	v_and_b32_e32 v11, 0xffff0000, v76
	v_lshlrev_b32_e32 v12, 16, v78
	s_waitcnt lgkmcnt(1)
	v_lshlrev_b32_e32 v8, 16, v0
	v_and_b32_e32 v9, 0xffff0000, v0
	v_pk_mul_f32 v[8:9], v[10:11], v[8:9]
	v_lshlrev_b32_e32 v0, 16, v1
	v_and_b32_e32 v1, 0xffff0000, v1
	v_lshlrev_b32_e32 v10, 16, v77
	v_and_b32_e32 v11, 0xffff0000, v77
	v_pk_mul_f32 v[10:11], v[10:11], v[0:1]
	v_lshlrev_b32_e32 v0, 16, v2
	v_and_b32_e32 v1, 0xffff0000, v2
	v_and_b32_e32 v13, 0xffff0000, v78
	v_pk_mul_f32 v[12:13], v[12:13], v[0:1]
	v_lshlrev_b32_e32 v0, 16, v3
	v_and_b32_e32 v1, 0xffff0000, v3
	v_lshlrev_b32_e32 v2, 16, v79
	v_and_b32_e32 v3, 0xffff0000, v79
	v_pk_mul_f32 v[14:15], v[2:3], v[0:1]
	v_cvt_pk_bf16_f32 v0, v8, v9
	v_lshlrev_b64 v[8:9], 11, v[126:127]
	v_lshl_add_u64 v[8:9], s[46:47], 0, v[8:9]
	v_lshl_add_u64 v[8:9], v[8:9], 0, s[52:53]
	v_cvt_pk_bf16_f32 v1, v10, v11
	v_cvt_pk_bf16_f32 v2, v12, v13
	v_cvt_pk_bf16_f32 v3, v14, v15
	v_lshl_add_u64 v[8:9], v[8:9], 0, v[124:125]
	global_store_dwordx4 v[8:9], v[0:3], off offset:1024
	v_lshlrev_b32_e32 v8, 16, v74
	v_and_b32_e32 v9, 0xffff0000, v74
	s_waitcnt lgkmcnt(0)
; #define LAS __attribute__((address_space(3)))
; __device__ __forceinline__ u32x4 pack8(const float (&f)[8]) { u32x4 w; w.x = pk_bf16(f[0], f[1]); w.y = pk_bf16(f[2], f[3]); w.z = pk_bf16(f[4], f[5]); w.w = pk_bf16(f[6], f[7]); return w; }
; template <bool SAMPLE> ...
;     ...
; #pragma unroll
;     for (int it4 = 0; it4 < 4; ++it4) {
;         const int qq = it4 * 8 + (lane >> 3), ch = lane & 7;
;         const int orow = SAMPLE ? row0 + (qq & 7) : row0 + qq;
;         const int ohead = SAMPLE ? head0 + (qq >> 3) : head0;
;         const u32x4 ow = *(const LAS u32x4*)(ost + qq * 64 + ch * 8);
;         float of[8], zf[8], yv[8];
;         unpack8(ow, of); unpack8(zw[it4], zf);
; #pragma unroll
;         for (int k = 0; k < 8; ++k) yv[k] = of[k] * zf[k];
;         *(u32x4*)(Y + (size_t)orow * D + 512 + ohead * 64 + ch * 8) = pack8(yv);
;     }
;     asm volatile("s_waitcnt lgkmcnt(0)" ::: "memory");
; __device__ __forceinline__ void attn_prompt_item(const Args& a, int l, int item, LAS unsigned char* lds, int tid, int lane, int wave) {
;     ...
;     attn_tile32<false>(qw1, zw1, Y, tab, qg, sinks, Kl + 32 * (qt0 + 1) * 144, Vl + 32 * (qt0 + 1) * 64, 16384, wsf, ost, rowq0 + 32, headw, b * 128 + qt0 * 32 + 32, (b == 0) ? 3 - qt0 : 0, lane);
;     __syncthreads();
	v_lshlrev_b32_e32 v0, 16, v4
	v_and_b32_e32 v1, 0xffff0000, v4
	v_lshlrev_b32_e32 v2, 16, v72
	v_and_b32_e32 v3, 0xffff0000, v72
	v_pk_mul_f32 v[0:1], v[2:3], v[0:1]
	v_lshlrev_b32_e32 v2, 16, v5
	v_and_b32_e32 v3, 0xffff0000, v5
	v_lshlrev_b32_e32 v4, 16, v73
	v_and_b32_e32 v5, 0xffff0000, v73
	v_pk_mul_f32 v[2:3], v[4:5], v[2:3]
	v_lshlrev_b32_e32 v4, 16, v6
	v_and_b32_e32 v5, 0xffff0000, v6
	v_pk_mul_f32 v[4:5], v[8:9], v[4:5]
	v_lshlrev_b32_e32 v6, 16, v7
	v_and_b32_e32 v7, 0xffff0000, v7
	v_lshlrev_b32_e32 v8, 16, v75
	v_and_b32_e32 v9, 0xffff0000, v75
	v_pk_mul_f32 v[6:7], v[8:9], v[6:7]
	v_or_b32_e32 v8, s73, v114
	v_ashrrev_i32_e32 v9, 31, v8
	v_cvt_pk_bf16_f32 v0, v0, v1
	v_cvt_pk_bf16_f32 v1, v2, v3
	v_cvt_pk_bf16_f32 v2, v4, v5
	v_lshlrev_b64 v[4:5], 11, v[8:9]
	v_cvt_pk_bf16_f32 v3, v6, v7
	v_lshl_add_u64 v[8:9], s[46:47], 0, v[4:5]
	ds_read_b128 v[4:7], v106
	v_lshl_add_u64 v[8:9], v[8:9], 0, s[52:53]
	v_lshl_add_u64 v[8:9], v[8:9], 0, v[124:125]
	global_store_dwordx4 v[8:9], v[0:3], off offset:1024
	ds_read_b128 v[0:3], v107
	s_waitcnt lgkmcnt(1)
	v_lshlrev_b32_e32 v8, 16, v4
	v_and_b32_e32 v9, 0xffff0000, v4
	v_lshlrev_b32_e32 v10, 16, v68
	v_and_b32_e32 v11, 0xffff0000, v68
	v_pk_mul_f32 v[8:9], v[10:11], v[8:9]
	v_lshlrev_b32_e32 v4, 16, v5
	v_and_b32_e32 v5, 0xffff0000, v5
	v_lshlrev_b32_e32 v10, 16, v69
	v_and_b32_e32 v11, 0xffff0000, v69
	v_pk_mul_f32 v[10:11], v[10:11], v[4:5]
	v_lshlrev_b32_e32 v4, 16, v6
	v_and_b32_e32 v5, 0xffff0000, v6
	v_lshlrev_b32_e32 v12, 16, v70
	v_and_b32_e32 v13, 0xffff0000, v70
	v_or_b32_e32 v16, s73, v104
	v_pk_mul_f32 v[12:13], v[12:13], v[4:5]
	v_lshlrev_b32_e32 v4, 16, v7
	v_and_b32_e32 v5, 0xffff0000, v7
	v_lshlrev_b32_e32 v6, 16, v71
	v_and_b32_e32 v7, 0xffff0000, v71
	v_ashrrev_i32_e32 v17, 31, v16
	v_pk_mul_f32 v[14:15], v[6:7], v[4:5]
	v_cvt_pk_bf16_f32 v4, v8, v9
	v_lshlrev_b64 v[8:9], 11, v[16:17]
	v_lshl_add_u64 v[8:9], s[46:47], 0, v[8:9]
	v_lshl_add_u64 v[8:9], v[8:9], 0, s[52:53]
	v_cvt_pk_bf16_f32 v5, v10, v11
	v_cvt_pk_bf16_f32 v6, v12, v13
	v_cvt_pk_bf16_f32 v7, v14, v15
	v_lshl_add_u64 v[8:9], v[8:9], 0, v[124:125]
	global_store_dwordx4 v[8:9], v[4:7], off offset:1024
	v_lshlrev_b32_e32 v8, 16, v66
	v_and_b32_e32 v9, 0xffff0000, v66
	s_waitcnt lgkmcnt(0)
	v_lshlrev_b32_e32 v4, 16, v0
	v_and_b32_e32 v5, 0xffff0000, v0
	v_lshlrev_b32_e32 v6, 16, v64
	v_and_b32_e32 v7, 0xffff0000, v64
	v_pk_mul_f32 v[4:5], v[6:7], v[4:5]
	v_lshlrev_b32_e32 v0, 16, v1
	v_and_b32_e32 v1, 0xffff0000, v1
	v_lshlrev_b32_e32 v6, 16, v65
	v_and_b32_e32 v7, 0xffff0000, v65
	v_pk_mul_f32 v[6:7], v[6:7], v[0:1]
	v_lshlrev_b32_e32 v0, 16, v2
	v_and_b32_e32 v1, 0xffff0000, v2
	v_or_b32_e32 v12, s73, v105
	v_pk_mul_f32 v[8:9], v[8:9], v[0:1]
	v_lshlrev_b32_e32 v0, 16, v3
	v_and_b32_e32 v1, 0xffff0000, v3
	v_lshlrev_b32_e32 v2, 16, v67
	v_and_b32_e32 v3, 0xffff0000, v67
	v_ashrrev_i32_e32 v13, 31, v12
	v_pk_mul_f32 v[10:11], v[2:3], v[0:1]
	v_cvt_pk_bf16_f32 v0, v4, v5
	v_lshlrev_b64 v[4:5], 11, v[12:13]
	v_lshl_add_u64 v[4:5], s[46:47], 0, v[4:5]
	v_lshl_add_u64 v[4:5], v[4:5], 0, s[52:53]
	v_cvt_pk_bf16_f32 v1, v6, v7
	v_cvt_pk_bf16_f32 v2, v8, v9
	v_cvt_pk_bf16_f32 v3, v10, v11
	v_lshl_add_u64 v[4:5], v[4:5], 0, v[124:125]
	global_store_dwordx4 v[4:5], v[0:3], off offset:1024
	s_waitcnt lgkmcnt(0)
	s_mov_b64 s[26:27], 0x1000
	s_barrier
	s_cbranch_scc1 .LBB0_444

; #define LAS __attribute__((address_space(3)))
; __device__ __forceinline__ s16x4 vtr(const LAS unsigned char* p) { return __builtin_bit_cast(s16x4, __builtin_amdgcn_ds_read_tr16_b64_v4i16((LAS v4i16_t*)p)); }
; template <bool SAMPLE> ...
;     ...
;     u32x4 pw[5][2];
; #pragma unroll
;     for (int t = 0; t < 5; ++t) {
; #pragma unroll
;         for (int i = 0; i < 16; ++i) { p[t][i] = __builtin_amdgcn_exp2f(p[t][i] - mx); lsum += p[t][i]; }
; #pragma unroll
;         for (int s = 0; s < 2; ++s) { pw[t][s].x = pk_bf16(p[t][8 * s + 0], p[t][8 * s + 1]); pw[t][s].y = pk_bf16(p[t][8 * s + 2], p[t][8 * s + 3]); pw[t][s].z = pk_bf16(p[t][8 * s + 4], p[t][8 * s + 5]); pw[t][s].w = pk_bf16(p[t][8 * s + 6], p[t][8 * s + 7]); }
;     }
;     lsum += __shfl_xor(lsum, 32);
;     const float denom = lsum + __builtin_amdgcn_exp2f(sk - mx);
;     if (hi == 0) wsf[r32] = 1.0f / denom;
;     __builtin_amdgcn_sched_barrier(0);
;     f32x16 o[2];
; #pragma unroll
;     for (int d0 = 0; d0 < 2; ++d0)
; #pragma unroll
;         for (int i = 0; i < 16; ++i) o[d0][i] = 0.f;
;     const int i16 = lane & 15;
;     const LAS unsigned char* vb = Vl + (4 * hi + (i16 >> 2)) * 64 + ((lane >> 4) & 1) * 32 + (i16 & 3) * 8;
; #pragma unroll
;     for (int t = 0; t < 5; ++t)
; #pragma unroll
;         for (int s = 0; s < 2; ++s) {
;             const bf16x8 pa = __builtin_bit_cast(bf16x8, pw[t][s]);
; #pragma unroll
;             for (int d0 = 0; d0 < 2; ++d0) {
;                 const s16x4 vlo = vtr(vb + d0 * vhalf + (32 * t + 16 * s) * 64), vhi = vtr(vb + d0 * vhalf + (32 * t + 16 * s + 8) * 64);
;                 const bf16x8 vf = (bf16x8){vlo[0], vlo[1], vlo[2], vlo[3], vhi[0], vhi[1], vhi[2], vhi[3]};
;                 o[d0] = __builtin_amdgcn_mfma_f32_32x32x16_bf16(pa, vf, o[d0], 0, 0, 0);
;             }
;         }
.LBB0_487:
	s_or_b64 exec, exec, s[94:95]
	v_lshl_add_u64 v[48:49], s[62:63], 0, v[172:173]
	v_cvt_pk_bf16_f32 v32, v32, v33
	v_cvt_pk_bf16_f32 v33, v34, v35
	v_cvt_pk_bf16_f32 v34, v141, v142
	v_cvt_pk_bf16_f32 v35, v143, v144
	v_cvt_pk_bf16_f32 v36, v36, v37
	v_cvt_pk_bf16_f32 v37, v38, v39
	v_cvt_pk_bf16_f32 v38, v137, v138
	v_cvt_pk_bf16_f32 v39, v139, v140
	v_cvt_pk_bf16_f32 v40, v40, v41
	v_cvt_pk_bf16_f32 v41, v42, v43
	v_cvt_pk_bf16_f32 v43, v46, v47
	v_cvt_pk_bf16_f32 v46, v120, v121
	v_cvt_pk_bf16_f32 v47, v122, v123
	v_cvt_pk_bf16_f32 v120, v24, v25
	v_cvt_pk_bf16_f32 v121, v26, v27
	v_cvt_pk_bf16_f32 v122, v28, v29
	v_cvt_pk_bf16_f32 v123, v30, v31
	v_cvt_pk_bf16_f32 v138, v16, v17
	v_cvt_pk_bf16_f32 v139, v18, v19
	v_cvt_pk_bf16_f32 v140, v20, v21
	v_cvt_pk_bf16_f32 v141, v22, v23
	v_cvt_pk_bf16_f32 v142, v8, v9
	v_cvt_pk_bf16_f32 v143, v10, v11
	v_cvt_pk_bf16_f32 v144, v12, v13
	v_cvt_pk_bf16_f32 v145, v14, v15
	s_waitcnt lgkmcnt(0)
	v_ashrrev_i32_e32 v129, 31, v128
	v_mul_u32_u24_e32 v52, 0x90, v134
	v_lshrrev_b32_e32 v154, 2, v132
	v_cvt_pk_bf16_f32 v42, v44, v45
	v_cvt_pk_bf16_f32 v44, v116, v117
	v_cvt_pk_bf16_f32 v45, v118, v119
	v_cvt_pk_bf16_f32 v150, v0, v1
	v_cvt_pk_bf16_f32 v151, v2, v3
	v_cvt_pk_bf16_f32 v152, v4, v5
	v_cvt_pk_bf16_f32 v153, v6, v7
	v_cvt_pk_bf16_f32 v60, v59, v60
	v_cvt_pk_bf16_f32 v61, v61, v62
	v_cvt_pk_bf16_f32 v62, v63, v112
	v_cvt_pk_bf16_f32 v63, v114, v115
	v_cvt_pk_bf16_f32 v16, v50, v51
	v_cvt_pk_bf16_f32 v17, v53, v54
	v_cvt_pk_bf16_f32 v18, v55, v56
	v_cvt_pk_bf16_f32 v19, v57, v58
	v_and_or_b32 v0, v154, 3, v136
	v_lshlrev_b32_e32 v115, 6, v0
	v_lshlrev_b32_e32 v1, 1, v132
	v_add_u32_e32 v0, s60, v115
	v_and_b32_e32 v117, 32, v1
	v_and_b32_e32 v118, 24, v135
	v_add3_u32 v50, v0, v117, v118
	ds_read_b64_tr_b16 v[0:1], v50 offset:36864
	ds_read_b64_tr_b16 v[2:3], v50 offset:37376
	ds_read_b64_tr_b16 v[20:21], v50 offset:53248
	ds_read_b64_tr_b16 v[22:23], v50 offset:53760
	s_waitcnt lgkmcnt(2)
	v_mfma_f32_32x32x16_bf16 v[0:15], v[16:19], v[0:3], 0
	ds_read_b64_tr_b16 v[54:55], v50 offset:37888
	ds_read_b64_tr_b16 v[56:57], v50 offset:38400
	s_waitcnt lgkmcnt(2)
	v_mfma_f32_32x32x16_bf16 v[16:31], v[16:19], v[20:23], 0
	ds_read_b64_tr_b16 v[236:237], v50 offset:54272
	ds_read_b64_tr_b16 v[238:239], v50 offset:54784
	s_waitcnt lgkmcnt(2)
	v_mfma_f32_32x32x16_bf16 v[0:15], v[60:63], v[54:57], v[0:15]
	ds_read_b64_tr_b16 v[54:55], v50 offset:38912
	ds_read_b64_tr_b16 v[56:57], v50 offset:39424
	s_waitcnt lgkmcnt(2)
	v_mfma_f32_32x32x16_bf16 v[16:31], v[60:63], v[236:239], v[16:31]
	ds_read_b64_tr_b16 v[236:237], v50 offset:55296
	ds_read_b64_tr_b16 v[238:239], v50 offset:55808
	s_waitcnt lgkmcnt(2)
	v_mfma_f32_32x32x16_bf16 v[0:15], v[150:153], v[54:57], v[0:15]
	ds_read_b64_tr_b16 v[54:55], v50 offset:39936
	ds_read_b64_tr_b16 v[56:57], v50 offset:40448
	s_waitcnt lgkmcnt(2)
	v_mfma_f32_32x32x16_bf16 v[16:31], v[150:153], v[236:239], v[16:31]
	ds_read_b64_tr_b16 v[236:237], v50 offset:56320
	ds_read_b64_tr_b16 v[238:239], v50 offset:56832
	s_waitcnt lgkmcnt(2)
	v_mfma_f32_32x32x16_bf16 v[0:15], v[142:145], v[54:57], v[0:15]
	ds_read_b64_tr_b16 v[54:55], v50 offset:40960
	ds_read_b64_tr_b16 v[56:57], v50 offset:41472
	s_waitcnt lgkmcnt(2)
	v_mfma_f32_32x32x16_bf16 v[16:31], v[142:145], v[236:239], v[16:31]
	ds_read_b64_tr_b16 v[236:237], v50 offset:57344
	ds_read_b64_tr_b16 v[238:239], v50 offset:57856
	s_waitcnt lgkmcnt(2)
	v_mfma_f32_32x32x16_bf16 v[0:15], v[138:141], v[54:57], v[0:15]
	ds_read_b64_tr_b16 v[54:55], v50 offset:41984
	ds_read_b64_tr_b16 v[56:57], v50 offset:42496
	s_waitcnt lgkmcnt(2)
	v_mfma_f32_32x32x16_bf16 v[16:31], v[138:141], v[236:239], v[16:31]
	ds_read_b64_tr_b16 v[236:237], v50 offset:58368
	ds_read_b64_tr_b16 v[238:239], v50 offset:58880
	s_waitcnt lgkmcnt(2)
	v_mfma_f32_32x32x16_bf16 v[0:15], v[120:123], v[54:57], v[0:15]
	ds_read_b64_tr_b16 v[54:55], v50 offset:43008
	ds_read_b64_tr_b16 v[56:57], v50 offset:43520
	s_waitcnt lgkmcnt(2)
	v_mfma_f32_32x32x16_bf16 v[16:31], v[120:123], v[236:239], v[16:31]
	ds_read_b64_tr_b16 v[236:237], v50 offset:59392
	ds_read_b64_tr_b16 v[238:239], v50 offset:59904
	s_waitcnt lgkmcnt(2)
	v_mfma_f32_32x32x16_bf16 v[0:15], v[44:47], v[54:57], v[0:15]
	ds_read_b64_tr_b16 v[54:55], v50 offset:44032
	ds_read_b64_tr_b16 v[56:57], v50 offset:44544
	s_waitcnt lgkmcnt(2)
	v_mfma_f32_32x32x16_bf16 v[16:31], v[44:47], v[236:239], v[16:31]
	ds_read_b64_tr_b16 v[236:237], v50 offset:60416
	ds_read_b64_tr_b16 v[238:239], v50 offset:60928
	s_waitcnt lgkmcnt(2)
	v_mfma_f32_32x32x16_bf16 v[0:15], v[40:43], v[54:57], v[0:15]
	ds_read_b64_tr_b16 v[54:55], v50 offset:45056
	ds_read_b64_tr_b16 v[56:57], v50 offset:45568
	s_waitcnt lgkmcnt(2)
	v_mfma_f32_32x32x16_bf16 v[16:31], v[40:43], v[236:239], v[16:31]
	ds_read_b64_tr_b16 v[236:237], v50 offset:61440
	ds_read_b64_tr_b16 v[238:239], v50 offset:61952
	s_waitcnt lgkmcnt(2)
	v_mfma_f32_32x32x16_bf16 v[0:15], v[36:39], v[54:57], v[0:15]
	ds_read_b64_tr_b16 v[54:55], v50 offset:46080
	ds_read_b64_tr_b16 v[56:57], v50 offset:46592
	s_waitcnt lgkmcnt(2)
	v_mfma_f32_32x32x16_bf16 v[16:31], v[36:39], v[236:239], v[16:31]
	ds_read_b64_tr_b16 v[236:237], v50 offset:62464
	ds_read_b64_tr_b16 v[238:239], v50 offset:62976
	s_waitcnt lgkmcnt(2)
	v_mfma_f32_32x32x16_bf16 v[0:15], v[32:35], v[54:57], v[0:15]
	s_waitcnt lgkmcnt(0)
	v_mfma_f32_32x32x16_bf16 v[16:31], v[32:35], v[236:239], v[16:31]
	s_waitcnt lgkmcnt(0)
	v_lshl_add_u32 v112, v136, 2, s65
	ds_read_b128 v[32:35], v112
	ds_read_b128 v[36:39], v112 offset:32
	v_lshl_add_u32 v40, v134, 1, s64
	v_lshlrev_b32_e32 v41, 9, v125
	v_add_u32_e32 v116, v40, v41
	s_waitcnt lgkmcnt(1)
; #define LAS __attribute__((address_space(3)))
; __device__ __forceinline__ u32x4 pack8(const float (&f)[8]) { u32x4 w; w.x = pk_bf16(f[0], f[1]); w.y = pk_bf16(f[2], f[3]); w.z = pk_bf16(f[4], f[5]); w.w = pk_bf16(f[6], f[7]); return w; }
; __device__ __forceinline__ int crow(int r, int hi) { return (r & 3) + 8 * (r >> 2) + 4 * hi; }
; template <bool SAMPLE> ...
;     ...
; #pragma unroll
;     for (int i = 0; i < 16; ++i) {
;         const int qq = crow(i, hi);
;         const float rl = wsf[qq];
; #pragma unroll
;         for (int d0 = 0; d0 < 2; ++d0) ost[qq * 64 + d0 * 32 + r32] = (bf16_t)(pk_bf16(o[d0][i] * rl, 0.f) & 0xffffu);
;     }
;     asm volatile("s_waitcnt lgkmcnt(0)" ::: "memory");
; #pragma unroll
;     for (int it4 = 0; it4 < 4; ++it4) {
;         const int qq = it4 * 8 + (lane >> 3), ch = lane & 7;
;         const int orow = SAMPLE ? row0 + (qq & 7) : row0 + qq;
;         const int ohead = SAMPLE ? head0 + (qq >> 3) : head0;
;         const u32x4 ow = *(const LAS u32x4*)(ost + qq * 64 + ch * 8);
;         float of[8], zf[8], yv[8];
;         unpack8(ow, of); unpack8(zw[it4], zf);
; #pragma unroll
;         for (int k = 0; k < 8; ++k) yv[k] = of[k] * zf[k];
;         *(u32x4*)(Y + (size_t)orow * D + 512 + ohead * 64 + ch * 8) = pack8(yv);
	s_nop 0
	v_mul_f32_e32 v0, v0, v32
	v_cvt_pk_bf16_f32 v0, v0, s0
	ds_write_b16 v116, v0
	s_nop 0
	v_mul_f32_e32 v0, v16, v32
	v_cvt_pk_bf16_f32 v0, v0, s0
	v_lshlrev_b32_e32 v16, 7, v136
	ds_write_b16 v116, v0 offset:64
	v_or_b32_e32 v0, 0x80, v16
	v_add_u32_e32 v119, v40, v0
	v_mul_f32_e32 v0, v1, v33
	v_cvt_pk_bf16_f32 v0, v0, s0
	ds_write_b16 v119, v0
	v_mul_f32_e32 v0, v17, v33
	v_cvt_pk_bf16_f32 v0, v0, s0
	ds_write_b16 v119, v0 offset:64
	v_or_b32_e32 v0, 0x100, v16
	v_add_u32_e32 v120, v40, v0
	v_mul_f32_e32 v0, v2, v34
	v_cvt_pk_bf16_f32 v0, v0, s0
	ds_write_b16 v120, v0
	v_mul_f32_e32 v0, v18, v34
	v_cvt_pk_bf16_f32 v0, v0, s0
	ds_write_b16 v120, v0 offset:64
	v_or_b32_e32 v0, 0x180, v16
	v_add_u32_e32 v121, v40, v0
	v_mul_f32_e32 v0, v3, v35
	v_cvt_pk_bf16_f32 v0, v0, s0
	ds_write_b16 v121, v0
	v_mul_f32_e32 v0, v19, v35
	v_cvt_pk_bf16_f32 v0, v0, s0
	ds_write_b16 v121, v0 offset:64
	v_or_b32_e32 v0, 0x400, v16
	v_add_u32_e32 v122, v40, v0
	s_waitcnt lgkmcnt(8)
	v_mul_f32_e32 v0, v4, v36
	v_cvt_pk_bf16_f32 v0, v0, s0
	ds_write_b16 v122, v0
	v_mul_f32_e32 v0, v20, v36
	v_cvt_pk_bf16_f32 v0, v0, s0
	ds_write_b16 v122, v0 offset:64
	v_or_b32_e32 v0, 0x480, v16
	v_add_u32_e32 v123, v40, v0
	v_mul_f32_e32 v0, v5, v37
	v_cvt_pk_bf16_f32 v0, v0, s0
	ds_write_b16 v123, v0
	v_mul_f32_e32 v0, v21, v37
	v_cvt_pk_bf16_f32 v0, v0, s0
	ds_write_b16 v123, v0 offset:64
	v_or_b32_e32 v0, 0x500, v16
	v_add_u32_e32 v135, v40, v0
	v_mul_f32_e32 v0, v6, v38
	v_cvt_pk_bf16_f32 v0, v0, s0
	ds_write_b16 v135, v0
	v_mul_f32_e32 v0, v22, v38
	v_cvt_pk_bf16_f32 v0, v0, s0
	ds_write_b16 v135, v0 offset:64
	v_or_b32_e32 v0, 0x580, v16
	v_add_u32_e32 v134, v40, v0
	v_mul_f32_e32 v0, v7, v39
	v_cvt_pk_bf16_f32 v0, v0, s0
	ds_write_b16 v134, v0
	v_mul_f32_e32 v0, v23, v39
	v_cvt_pk_bf16_f32 v4, v0, s0
	ds_read_b128 v[0:3], v112 offset:64
	ds_write_b16 v134, v4 offset:64
	ds_read_b128 v[4:7], v112 offset:96
	v_or_b32_e32 v17, 0x800, v16
	v_add_u32_e32 v136, v40, v17
	s_waitcnt lgkmcnt(2)
	v_mul_f32_e32 v8, v8, v0
	v_mul_f32_e32 v0, v24, v0
	v_cvt_pk_bf16_f32 v0, v0, s0
	ds_write_b16 v136, v0 offset:64
	v_or_b32_e32 v0, 0x880, v16
	v_add_u32_e32 v137, v40, v0
	v_mul_f32_e32 v0, v9, v1
	v_cvt_pk_bf16_f32 v0, v0, s0
	ds_write_b16 v137, v0
	v_mul_f32_e32 v0, v25, v1
	v_cvt_pk_bf16_f32 v0, v0, s0
	ds_write_b16 v137, v0 offset:64
	v_or_b32_e32 v0, 0x900, v16
	v_add_u32_e32 v138, v40, v0
	v_mul_f32_e32 v0, v10, v2
	v_cvt_pk_bf16_f32 v0, v0, s0
	ds_write_b16 v138, v0
	v_mul_f32_e32 v0, v26, v2
	v_cvt_pk_bf16_f32 v0, v0, s0
	ds_write_b16 v138, v0 offset:64
	v_or_b32_e32 v0, 0x980, v16
	v_add_u32_e32 v139, v40, v0
	v_mul_f32_e32 v0, v11, v3
	v_cvt_pk_bf16_f32 v0, v0, s0
	ds_write_b16 v139, v0
	v_mul_f32_e32 v0, v27, v3
	v_cvt_pk_bf16_f32 v0, v0, s0
	ds_write_b16 v139, v0 offset:64
	v_or_b32_e32 v0, 0xc00, v16
	v_add_u32_e32 v140, v40, v0
	s_waitcnt lgkmcnt(7)
	v_mul_f32_e32 v0, v12, v4
	v_cvt_pk_bf16_f32 v0, v0, s0
	ds_write_b16 v140, v0
	v_mul_f32_e32 v0, v28, v4
	v_cvt_pk_bf16_f32 v0, v0, s0
	ds_write_b16 v140, v0 offset:64
	v_or_b32_e32 v0, 0xc80, v16
	v_add_u32_e32 v141, v40, v0
	v_mul_f32_e32 v0, v13, v5
	v_cvt_pk_bf16_f32 v0, v0, s0
	ds_write_b16 v141, v0
	v_mul_f32_e32 v0, v29, v5
	v_cvt_pk_bf16_f32 v0, v0, s0
	ds_write_b16 v141, v0 offset:64
	v_or_b32_e32 v0, 0xd00, v16
	v_add_u32_e32 v142, v40, v0
	v_mul_f32_e32 v0, v14, v6
	v_cvt_pk_bf16_f32 v0, v0, s0
	ds_write_b16 v142, v0
	v_mul_f32_e32 v0, v30, v6
	v_cvt_pk_bf16_f32 v0, v0, s0
	ds_write_b16 v142, v0 offset:64
	v_or_b32_e32 v0, 0xd80, v16
	v_add_u32_e32 v143, v40, v0
	v_mul_f32_e32 v0, v15, v7
	v_cvt_pk_bf16_f32 v0, v0, s0
	ds_write_b16 v143, v0
	v_mul_f32_e32 v0, v31, v7
	v_cvt_pk_bf16_f32 v8, v8, s0
	v_cvt_pk_bf16_f32 v0, v0, s0
	ds_write_b16 v136, v8
	ds_write_b16 v143, v0 offset:64
	v_add_u32_e32 v16, s64, v124
	v_lshlrev_b32_e32 v0, 7, v133
	s_waitcnt lgkmcnt(0)
	v_add_u32_e32 v144, v16, v0
	ds_read_b128 v[0:3], v144
	v_or_b32_e32 v114, 8, v133
	v_lshlrev_b32_e32 v4, 7, v114
	v_add_u32_e32 v145, v16, v4
	ds_read_b128 v[4:7], v145
	s_waitcnt lgkmcnt(1)
	v_lshlrev_b32_e32 v8, 16, v0
	v_and_b32_e32 v9, 0xffff0000, v0
	v_lshlrev_b32_e32 v10, 16, v108
	v_and_b32_e32 v11, 0xffff0000, v108
	v_pk_mul_f32 v[8:9], v[10:11], v[8:9]
	v_lshlrev_b32_e32 v0, 16, v1
	v_and_b32_e32 v1, 0xffff0000, v1
	v_lshlrev_b32_e32 v10, 16, v109
	v_and_b32_e32 v11, 0xffff0000, v109
	v_pk_mul_f32 v[10:11], v[10:11], v[0:1]
	v_lshlrev_b32_e32 v0, 16, v2
	v_and_b32_e32 v1, 0xffff0000, v2
	v_lshlrev_b32_e32 v12, 16, v110
	v_and_b32_e32 v13, 0xffff0000, v110
	v_pk_mul_f32 v[12:13], v[12:13], v[0:1]
	v_lshlrev_b32_e32 v0, 16, v3
	v_and_b32_e32 v1, 0xffff0000, v3
	v_lshlrev_b32_e32 v2, 16, v111
	v_and_b32_e32 v3, 0xffff0000, v111
	v_pk_mul_f32 v[14:15], v[2:3], v[0:1]
	v_cvt_pk_bf16_f32 v0, v8, v9
	v_lshlrev_b64 v[8:9], 11, v[128:129]
	v_lshl_add_u64 v[8:9], s[46:47], 0, v[8:9]
	v_lshl_add_u64 v[8:9], v[8:9], 0, s[52:53]
	v_mov_b32_e32 v125, v173
	v_cvt_pk_bf16_f32 v1, v10, v11
	v_cvt_pk_bf16_f32 v2, v12, v13
	v_cvt_pk_bf16_f32 v3, v14, v15
	v_lshl_add_u64 v[8:9], v[8:9], 0, v[124:125]
	global_store_dwordx4 v[8:9], v[0:3], off offset:1024
	v_lshlrev_b32_e32 v8, 16, v106
	v_and_b32_e32 v9, 0xffff0000, v106
	s_waitcnt lgkmcnt(0)
; #define LAS __attribute__((address_space(3)))
; __device__ __forceinline__ u32x4 pack8(const float (&f)[8]) { u32x4 w; w.x = pk_bf16(f[0], f[1]); w.y = pk_bf16(f[2], f[3]); w.z = pk_bf16(f[4], f[5]); w.w = pk_bf16(f[6], f[7]); return w; }
; template <bool SAMPLE> ...
;     ...
;     float q[4][8];
; #pragma unroll
;     for (int d0 = 0; d0 < 4; ++d0) unpack8(qw[d0], q[d0]);
;     float ss = 0.f;
; #pragma unroll
;     for (int d0 = 0; d0 < 4; ++d0)
; #pragma unroll
;         for (int i = 0; i < 8; ++i) ss += q[d0][i] * q[d0][i];
;     ss += __shfl_xor(ss, 32);
;     ...
; #pragma unroll
;     for (int it4 = 0; it4 < 4; ++it4) {
;         const int qq = it4 * 8 + (lane >> 3), ch = lane & 7;
;         const int orow = SAMPLE ? row0 + (qq & 7) : row0 + qq;
;         const int ohead = SAMPLE ? head0 + (qq >> 3) : head0;
;         const u32x4 ow = *(const LAS u32x4*)(ost + qq * 64 + ch * 8);
;         float of[8], zf[8], yv[8];
;         unpack8(ow, of); unpack8(zw[it4], zf);
; #pragma unroll
;         for (int k = 0; k < 8; ++k) yv[k] = of[k] * zf[k];
;         *(u32x4*)(Y + (size_t)orow * D + 512 + ohead * 64 + ch * 8) = pack8(yv);
;     }
	v_lshlrev_b32_e32 v0, 16, v4
	v_and_b32_e32 v1, 0xffff0000, v4
	v_lshlrev_b32_e32 v2, 16, v104
	v_and_b32_e32 v3, 0xffff0000, v104
	v_pk_mul_f32 v[0:1], v[2:3], v[0:1]
	v_lshlrev_b32_e32 v2, 16, v5
	v_and_b32_e32 v3, 0xffff0000, v5
	v_lshlrev_b32_e32 v4, 16, v105
	v_and_b32_e32 v5, 0xffff0000, v105
	v_pk_mul_f32 v[2:3], v[4:5], v[2:3]
	v_lshlrev_b32_e32 v4, 16, v6
	v_and_b32_e32 v5, 0xffff0000, v6
	v_pk_mul_f32 v[4:5], v[8:9], v[4:5]
	v_lshlrev_b32_e32 v6, 16, v7
	v_and_b32_e32 v7, 0xffff0000, v7
	v_lshlrev_b32_e32 v8, 16, v107
	v_and_b32_e32 v9, 0xffff0000, v107
	v_pk_mul_f32 v[6:7], v[8:9], v[6:7]
	v_or_b32_e32 v8, s92, v114
	v_ashrrev_i32_e32 v9, 31, v8
	v_cvt_pk_bf16_f32 v0, v0, v1
	v_cvt_pk_bf16_f32 v1, v2, v3
	v_cvt_pk_bf16_f32 v2, v4, v5
	v_lshlrev_b64 v[4:5], 11, v[8:9]
	v_lshl_add_u64 v[4:5], s[46:47], 0, v[4:5]
	v_lshl_add_u64 v[4:5], v[4:5], 0, s[52:53]
	v_cvt_pk_bf16_f32 v3, v6, v7
	v_lshl_add_u64 v[4:5], v[4:5], 0, v[124:125]
	v_or_b32_e32 v104, 16, v133
	global_store_dwordx4 v[4:5], v[0:3], off offset:1024
	v_or_b32_e32 v105, 24, v133
	v_lshlrev_b32_e32 v4, 7, v105
	v_lshlrev_b32_e32 v0, 7, v104
	v_add_u32_e32 v106, v16, v0
	ds_read_b128 v[0:3], v106
	v_add_u32_e32 v107, v16, v4
	ds_read_b128 v[4:7], v107
	v_lshlrev_b32_e32 v10, 16, v100
	v_and_b32_e32 v11, 0xffff0000, v100
	s_waitcnt lgkmcnt(1)
	v_lshlrev_b32_e32 v8, 16, v0
	v_and_b32_e32 v9, 0xffff0000, v0
	v_pk_mul_f32 v[8:9], v[10:11], v[8:9]
	v_lshlrev_b32_e32 v0, 16, v1
	v_and_b32_e32 v1, 0xffff0000, v1
	v_lshlrev_b32_e32 v10, 16, v101
	v_and_b32_e32 v11, 0xffff0000, v101
	v_pk_mul_f32 v[10:11], v[10:11], v[0:1]
	v_lshlrev_b32_e32 v0, 16, v2
	v_and_b32_e32 v1, 0xffff0000, v2
	v_lshlrev_b32_e32 v12, 16, v102
	v_and_b32_e32 v13, 0xffff0000, v102
	v_or_b32_e32 v16, s92, v104
	v_pk_mul_f32 v[12:13], v[12:13], v[0:1]
	v_lshlrev_b32_e32 v0, 16, v3
	v_and_b32_e32 v1, 0xffff0000, v3
	v_lshlrev_b32_e32 v2, 16, v103
	v_and_b32_e32 v3, 0xffff0000, v103
	v_ashrrev_i32_e32 v17, 31, v16
	v_pk_mul_f32 v[14:15], v[2:3], v[0:1]
	v_cvt_pk_bf16_f32 v0, v8, v9
	v_lshlrev_b64 v[8:9], 11, v[16:17]
	v_lshl_add_u64 v[8:9], s[46:47], 0, v[8:9]
	v_lshl_add_u64 v[8:9], v[8:9], 0, s[52:53]
	v_cvt_pk_bf16_f32 v1, v10, v11
	v_cvt_pk_bf16_f32 v2, v12, v13
	v_cvt_pk_bf16_f32 v3, v14, v15
	v_lshl_add_u64 v[8:9], v[8:9], 0, v[124:125]
	global_store_dwordx4 v[8:9], v[0:3], off offset:1024
	v_lshlrev_b32_e32 v8, 16, v98
	v_and_b32_e32 v9, 0xffff0000, v98
	s_waitcnt lgkmcnt(0)
	v_lshlrev_b32_e32 v0, 16, v4
	v_and_b32_e32 v1, 0xffff0000, v4
	v_lshlrev_b32_e32 v2, 16, v96
	v_and_b32_e32 v3, 0xffff0000, v96
	v_pk_mul_f32 v[0:1], v[2:3], v[0:1]
	v_lshlrev_b32_e32 v2, 16, v5
	v_and_b32_e32 v3, 0xffff0000, v5
	v_lshlrev_b32_e32 v4, 16, v97
	v_and_b32_e32 v5, 0xffff0000, v97
	v_pk_mul_f32 v[2:3], v[4:5], v[2:3]
	v_lshlrev_b32_e32 v4, 16, v6
	v_and_b32_e32 v5, 0xffff0000, v6
	v_pk_mul_f32 v[4:5], v[8:9], v[4:5]
	v_lshlrev_b32_e32 v6, 16, v7
	v_and_b32_e32 v7, 0xffff0000, v7
	v_lshlrev_b32_e32 v8, 16, v99
	v_and_b32_e32 v9, 0xffff0000, v99
	v_pk_mul_f32 v[6:7], v[8:9], v[6:7]
	v_or_b32_e32 v8, s92, v105
	v_ashrrev_i32_e32 v9, 31, v8
	v_cvt_pk_bf16_f32 v0, v0, v1
	v_cvt_pk_bf16_f32 v1, v2, v3
	v_cvt_pk_bf16_f32 v2, v4, v5
	v_lshlrev_b64 v[4:5], 11, v[8:9]
	v_lshl_add_u64 v[4:5], s[46:47], 0, v[4:5]
	v_lshl_add_u64 v[4:5], v[4:5], 0, s[52:53]
	v_cvt_pk_bf16_f32 v3, v6, v7
	v_lshl_add_u64 v[4:5], v[4:5], 0, v[124:125]
	global_store_dwordx4 v[4:5], v[0:3], off offset:1024
	s_waitcnt lgkmcnt(0)
	global_load_dwordx4 v[0:3], v[48:49], off
	global_load_dwordx4 v[4:7], v[48:49], off offset:16
	global_load_dwordx4 v[8:11], v[48:49], off offset:64
	global_load_dwordx4 v[12:15], v[48:49], off offset:80
	global_load_dwordx4 v[16:19], v[48:49], off offset:128
	global_load_dwordx4 v[20:23], v[48:49], off offset:144
	global_load_dwordx4 v[24:27], v[48:49], off offset:192
	global_load_dwordx4 v[28:31], v[48:49], off offset:208
	v_or_b32_e32 v32, s86, v132
	v_lshl_or_b32 v44, v32, 6, v224
	global_load_dwordx4 v[32:35], v44, s[48:49] offset:32
	global_load_dwordx4 v[36:39], v44, s[48:49] offset:48
	global_load_dwordx4 v[40:43], v44, s[48:49]
	s_nop 0
	global_load_dwordx4 v[44:47], v44, s[48:49] offset:16
	v_lshlrev_b32_e32 v166, 16, v80
	v_and_b32_e32 v167, 0xffff0000, v80
	v_lshlrev_b32_e32 v162, 16, v81
	v_and_b32_e32 v163, 0xffff0000, v81
	v_pk_mul_f32 v[80:81], v[166:167], v[166:167]
	v_pk_mul_f32 v[164:165], v[162:163], v[162:163]
	v_add_f32_e32 v53, v80, v81
	v_lshlrev_b32_e32 v160, 16, v82
	v_and_b32_e32 v161, 0xffff0000, v82
	v_add_f32_e32 v53, v164, v53
	v_lshlrev_b32_e32 v156, 16, v83
	v_and_b32_e32 v157, 0xffff0000, v83
	v_pk_mul_f32 v[82:83], v[160:161], v[160:161]
	v_add_f32_e32 v53, v165, v53
	v_add_f32_e32 v53, v82, v53
	v_pk_mul_f32 v[158:159], v[156:157], v[156:157]
	v_add_f32_e32 v53, v83, v53
	v_lshlrev_b32_e32 v154, 16, v84
	v_and_b32_e32 v155, 0xffff0000, v84
	v_add_f32_e32 v53, v158, v53
	v_lshlrev_b32_e32 v150, 16, v85
	v_and_b32_e32 v151, 0xffff0000, v85
	v_pk_mul_f32 v[84:85], v[154:155], v[154:155]
	v_add_f32_e32 v53, v159, v53
	v_add_f32_e32 v53, v84, v53
	v_pk_mul_f32 v[152:153], v[150:151], v[150:151]
	v_add_f32_e32 v53, v85, v53
	v_lshlrev_b32_e32 v132, 16, v86
	v_and_b32_e32 v133, 0xffff0000, v86
	v_add_f32_e32 v53, v152, v53
	v_lshlrev_b32_e32 v110, 16, v87
	v_and_b32_e32 v111, 0xffff0000, v87
	v_pk_mul_f32 v[86:87], v[132:133], v[132:133]
	v_add_f32_e32 v53, v153, v53
	v_add_f32_e32 v53, v86, v53
	v_pk_mul_f32 v[128:129], v[110:111], v[110:111]
	v_add_f32_e32 v53, v87, v53
	v_lshlrev_b32_e32 v108, 16, v88
	v_and_b32_e32 v109, 0xffff0000, v88
	v_add_f32_e32 v53, v128, v53
	v_lshlrev_b32_e32 v100, 16, v89
; __device__ __forceinline__ u32x4 pack8(const float (&f)[8]) { u32x4 w; w.x = pk_bf16(f[0], f[1]); w.y = pk_bf16(f[2], f[3]); w.z = pk_bf16(f[4], f[5]); w.w = pk_bf16(f[6], f[7]); return w; }
; template <bool SAMPLE> ...
;     ...
;     float ss = 0.f;
; #pragma unroll
;     for (int d0 = 0; d0 < 4; ++d0)
; #pragma unroll
;         for (int i = 0; i < 8; ++i) ss += q[d0][i] * q[d0][i];
;     ss += __shfl_xor(ss, 32);
;     const float rstd = rsqrtf(ss * (1.0f / 64.0f) + EPS);
; #pragma unroll
;     for (int d0 = 0; d0 < 4; ++d0) { const f32x4 g0 = *(const f32x4*)(qg + d0 * 16 + hi * 8), g1 = *(const f32x4*)(qg + d0 * 16 + hi * 8 + 4);
;         q[d0][0] *= rstd * g0.x; q[d0][1] *= rstd * g0.y; q[d0][2] *= rstd * g0.z; q[d0][3] *= rstd * g0.w; q[d0][4] *= rstd * g1.x; q[d0][5] *= rstd * g1.y; q[d0][6] *= rstd * g1.z; q[d0][7] *= rstd * g1.w; }
;     {
;         const float* tr = tab + (size_t)mypos * 16;
;         const f32x4 c0 = *(const f32x4*)(tr), c1 = *(const f32x4*)(tr + 4), s0 = *(const f32x4*)(tr + 8), s1 = *(const f32x4*)(tr + 12);
;         const float cs[8] = {c0.x, c0.y, c0.z, c0.w, c1.x, c1.y, c1.z, c1.w}, sn[8] = {s0.x, s0.y, s0.z, s0.w, s1.x, s1.y, s1.z, s1.w};
;         const float sg = (hi == 0) ? -1.0f : 1.0f;
; #pragma unroll
;         for (int i = 0; i < 8; ++i) { const float pr = __shfl_xor(q[0][i], 32); q[0][i] = q[0][i] * cs[i] + sg * pr * sn[i]; }
;     }
;     bf16x8 qr[4];
; #pragma unroll
;     for (int d0 = 0; d0 < 4; ++d0) {
; #pragma unroll
;         for (int i = 0; i < 8; ++i) q[d0][i] *= 0.125f * LOG2E;
;         qr[d0] = __builtin_bit_cast(bf16x8, pack8(q[d0])); }
;     f32x16 p[5];
;     const int rq = SAMPLE ? (r32 & 7) : r32;
;     const int lo = rq + 1 - 4 * hi, hi_ = rq - 4 * hi;
;     float mx = -1e30f;
	v_and_b32_e32 v101, 0xffff0000, v89
	v_pk_mul_f32 v[88:89], v[108:109], v[108:109]
	v_add_f32_e32 v53, v129, v53
	v_add_f32_e32 v53, v88, v53
	v_pk_mul_f32 v[102:103], v[100:101], v[100:101]
	v_add_f32_e32 v53, v89, v53
	v_lshlrev_b32_e32 v98, 16, v90
	v_and_b32_e32 v99, 0xffff0000, v90
	v_add_f32_e32 v53, v102, v53
	v_lshlrev_b32_e32 v48, 16, v95
	v_and_b32_e32 v49, 0xffff0000, v95
	v_lshlrev_b32_e32 v54, 16, v94
	v_and_b32_e32 v55, 0xffff0000, v94
	v_lshlrev_b32_e32 v94, 16, v91
	v_and_b32_e32 v95, 0xffff0000, v91
	v_pk_mul_f32 v[90:91], v[98:99], v[98:99]
	v_add_f32_e32 v53, v103, v53
	v_add_f32_e32 v53, v90, v53
	v_pk_mul_f32 v[96:97], v[94:95], v[94:95]
	v_add_f32_e32 v53, v91, v53
	v_lshlrev_b32_e32 v62, 16, v92
	v_and_b32_e32 v63, 0xffff0000, v92
	v_add_f32_e32 v53, v96, v53
	v_lshlrev_b32_e32 v58, 16, v93
	v_and_b32_e32 v59, 0xffff0000, v93
	v_pk_mul_f32 v[92:93], v[62:63], v[62:63]
	v_add_f32_e32 v53, v97, v53
	v_add_f32_e32 v53, v92, v53
	v_pk_mul_f32 v[60:61], v[58:59], v[58:59]
	v_add_f32_e32 v53, v93, v53
	v_add_f32_e32 v53, v60, v53
	v_pk_mul_f32 v[56:57], v[54:55], v[54:55]
	v_add_f32_e32 v53, v61, v53
	v_add_f32_e32 v53, v56, v53
	v_pk_mul_f32 v[50:51], v[48:49], v[48:49]
	v_add_f32_e32 v53, v57, v53
	v_add_f32_e32 v50, v50, v53
	v_add_f32_e32 v50, v51, v50
	ds_bpermute_b32 v51, v127, v50
	v_mov_b32_e32 v102, 0xf149f2ca
	v_mov_b32_e32 v97, 0xf149f2ca
	v_mov_b32_e32 v92, 0xf149f2ca
	v_mov_b32_e32 v93, 0xf149f2ca
	s_waitcnt lgkmcnt(0)
	v_add_f32_e32 v50, v50, v51
	v_fmamk_f32 v50, v50, 0x3c800000, v209
	v_mul_f32_e32 v51, 0x4b800000, v50
	v_cmp_gt_f32_e32 vcc, s96, v50
	v_mov_b32_e32 v96, 0xf149f2ca
	v_mov_b32_e32 v103, 0xf149f2ca
	v_cndmask_b32_e32 v50, v50, v51, vcc
	v_rsq_f32_e32 v50, v50
	s_nop 0
	v_mul_f32_e32 v51, 0x45800000, v50
	v_cndmask_b32_e32 v50, v50, v51, vcc
	s_waitcnt vmcnt(11)
	v_pk_mul_f32 v[0:1], v[0:1], v[50:51] op_sel_hi:[1,0]
	v_pk_mul_f32 v[2:3], v[2:3], v[50:51] op_sel_hi:[1,0]
	v_pk_mul_f32 v[0:1], v[0:1], v[166:167]
	s_waitcnt vmcnt(10)
	v_pk_mul_f32 v[4:5], v[4:5], v[50:51] op_sel_hi:[1,0]
	v_pk_mul_f32 v[6:7], v[6:7], v[50:51] op_sel_hi:[1,0]
	s_waitcnt vmcnt(9)
	v_pk_mul_f32 v[8:9], v[8:9], v[50:51] op_sel_hi:[1,0]
	v_pk_mul_f32 v[10:11], v[10:11], v[50:51] op_sel_hi:[1,0]
	s_waitcnt vmcnt(8)
	v_pk_mul_f32 v[12:13], v[12:13], v[50:51] op_sel_hi:[1,0]
	v_pk_mul_f32 v[14:15], v[14:15], v[50:51] op_sel_hi:[1,0]
	s_waitcnt vmcnt(7)
	v_pk_mul_f32 v[16:17], v[16:17], v[50:51] op_sel_hi:[1,0]
	v_pk_mul_f32 v[18:19], v[18:19], v[50:51] op_sel_hi:[1,0]
	s_waitcnt vmcnt(6)
	v_pk_mul_f32 v[20:21], v[20:21], v[50:51] op_sel_hi:[1,0]
	v_pk_mul_f32 v[22:23], v[22:23], v[50:51] op_sel_hi:[1,0]
	s_waitcnt vmcnt(5)
	v_pk_mul_f32 v[24:25], v[24:25], v[50:51] op_sel_hi:[1,0]
	v_pk_mul_f32 v[26:27], v[26:27], v[50:51] op_sel_hi:[1,0]
	s_waitcnt vmcnt(4)
	v_pk_mul_f32 v[28:29], v[28:29], v[50:51] op_sel_hi:[1,0]
	ds_bpermute_b32 v51, v127, v1
	ds_bpermute_b32 v53, v127, v0
	v_pk_mul_f32 v[2:3], v[2:3], v[162:163]
	v_pk_mul_f32 v[4:5], v[4:5], v[160:161]
	v_pk_mul_f32 v[6:7], v[6:7], v[156:157]
	s_waitcnt lgkmcnt(1)
	v_pk_mul_f32 v[30:31], v[30:31], v[50:51] op_sel_hi:[1,0]
	ds_bpermute_b32 v50, v127, v3
	v_pk_mul_f32 v[30:31], v[30:31], v[48:49]
	v_cndmask_b32_e64 v49, v51, -v51, s[0:1]
	ds_bpermute_b32 v51, v127, v2
	s_waitcnt lgkmcnt(2)
	v_cndmask_b32_e64 v48, v53, -v53, s[0:1]
	s_waitcnt vmcnt(3)
	v_pk_mul_f32 v[32:33], v[32:33], v[48:49]
	v_pk_mul_f32 v[8:9], v[8:9], v[154:155]
	s_waitcnt vmcnt(1)
	v_pk_fma_f32 v[0:1], v[40:41], v[0:1], v[32:33]
	ds_bpermute_b32 v40, v127, v5
	s_waitcnt lgkmcnt(2)
	v_cndmask_b32_e64 v33, v50, -v50, s[0:1]
	s_waitcnt lgkmcnt(1)
	v_cndmask_b32_e64 v32, v51, -v51, s[0:1]
	v_pk_mul_f32 v[32:33], v[34:35], v[32:33]
	ds_bpermute_b32 v34, v127, v4
	v_pk_fma_f32 v[2:3], v[42:43], v[2:3], v[32:33]
	s_waitcnt lgkmcnt(1)
	v_cndmask_b32_e64 v33, v40, -v40, s[0:1]
	ds_bpermute_b32 v35, v127, v7
	ds_bpermute_b32 v40, v127, v6
	s_waitcnt lgkmcnt(2)
	v_cndmask_b32_e64 v32, v34, -v34, s[0:1]
	v_pk_mul_f32 v[32:33], v[36:37], v[32:33]
	v_pk_mul_f32 v[10:11], v[10:11], v[150:151]
	s_waitcnt vmcnt(0)
	v_pk_fma_f32 v[4:5], v[44:45], v[4:5], v[32:33]
	s_waitcnt lgkmcnt(1)
	v_cndmask_b32_e64 v33, v35, -v35, s[0:1]
	s_waitcnt lgkmcnt(0)
	v_cndmask_b32_e64 v32, v40, -v40, s[0:1]
	v_pk_mul_f32 v[32:33], v[38:39], v[32:33]
	v_pk_mul_f32 v[12:13], v[12:13], v[132:133]
	v_pk_fma_f32 v[6:7], v[46:47], v[6:7], v[32:33]
	v_pk_mul_f32 v[14:15], v[14:15], v[110:111]
	v_pk_mul_f32 v[0:1], v[0:1], s[90:91] op_sel_hi:[1,0]
	v_pk_mul_f32 v[2:3], v[2:3], s[90:91] op_sel_hi:[1,0]
	v_pk_mul_f32 v[4:5], v[4:5], s[90:91] op_sel_hi:[1,0]
	v_pk_mul_f32 v[6:7], v[6:7], s[90:91] op_sel_hi:[1,0]
	v_pk_mul_f32 v[16:17], v[16:17], v[108:109]
	v_pk_mul_f32 v[18:19], v[18:19], v[100:101]
	v_pk_mul_f32 v[20:21], v[20:21], v[98:99]
	v_pk_mul_f32 v[22:23], v[22:23], v[94:95]
	v_cvt_pk_bf16_f32 v48, v0, v1
	v_cvt_pk_bf16_f32 v49, v2, v3
	v_cvt_pk_bf16_f32 v50, v4, v5
	v_cvt_pk_bf16_f32 v51, v6, v7
	v_pk_mul_f32 v[0:1], v[8:9], s[90:91] op_sel_hi:[1,0]
	v_pk_mul_f32 v[2:3], v[10:11], s[90:91] op_sel_hi:[1,0]
	v_pk_mul_f32 v[4:5], v[12:13], s[90:91] op_sel_hi:[1,0]
	v_pk_mul_f32 v[6:7], v[14:15], s[90:91] op_sel_hi:[1,0]
	v_pk_mul_f32 v[24:25], v[24:25], v[62:63]
	v_pk_mul_f32 v[26:27], v[26:27], v[58:59]
	v_pk_mul_f32 v[28:29], v[28:29], v[54:55]
	v_cvt_pk_bf16_f32 v80, v0, v1
	v_cvt_pk_bf16_f32 v81, v2, v3
	v_cvt_pk_bf16_f32 v82, v4, v5
	v_cvt_pk_bf16_f32 v83, v6, v7
	v_pk_mul_f32 v[0:1], v[16:17], s[90:91] op_sel_hi:[1,0]
	v_pk_mul_f32 v[2:3], v[18:19], s[90:91] op_sel_hi:[1,0]
	v_pk_mul_f32 v[4:5], v[20:21], s[90:91] op_sel_hi:[1,0]
	v_pk_mul_f32 v[6:7], v[22:23], s[90:91] op_sel_hi:[1,0]
	v_cvt_pk_bf16_f32 v84, v0, v1
	v_cvt_pk_bf16_f32 v85, v2, v3
	v_cvt_pk_bf16_f32 v86, v4, v5
	v_cvt_pk_bf16_f32 v87, v6, v7
	v_pk_mul_f32 v[0:1], v[24:25], s[90:91] op_sel_hi:[1,0]
	v_pk_mul_f32 v[2:3], v[26:27], s[90:91] op_sel_hi:[1,0]
	v_pk_mul_f32 v[4:5], v[28:29], s[90:91] op_sel_hi:[1,0]
	v_pk_mul_f32 v[6:7], v[30:31], s[90:91] op_sel_hi:[1,0]
	v_add_u32_e32 v32, s82, v149
	v_cvt_pk_bf16_f32 v88, v0, v1
	v_cvt_pk_bf16_f32 v89, v2, v3
	v_cvt_pk_bf16_f32 v90, v4, v5
	v_cvt_pk_bf16_f32 v91, v6, v7
	v_mov_b32_e32 v0, 0xf149f2ca
	s_and_b64 vcc, exec, s[38:39]
	v_add_u32_e32 v125, v32, v52
	v_mov_b32_e32 v100, 0xf149f2ca
	v_mov_b32_e32 v99, 0xf149f2ca
	v_mov_b32_e32 v94, 0xf149f2ca
	v_mov_b32_e32 v95, 0xf149f2ca
	v_mov_b32_e32 v98, 0xf149f2ca
	v_mov_b32_e32 v101, 0xf149f2ca
	v_mov_b32_e32 v108, 0xf149f2ca
	v_mov_b32_e32 v109, 0xf149f2ca
	v_mov_b32_e32 v110, 0xf149f2ca
	v_mov_b32_e32 v111, 0xf149f2ca
	s_cbranch_vccnz .LBB0_489
; #define LAS __attribute__((address_space(3)))
; template <bool SAMPLE> ...
;     ...
;     for (int t = 0; t < 5; ++t) {
;         if (t >= tmin) {
; #pragma unroll
;             for (int i = 0; i < 16; ++i) p[t][i] = 0.f;
; #pragma unroll
;             for (int d0 = 0; d0 < 4; ++d0) { const bf16x8 kf = *(const LAS bf16x8*)(Kl + (32 * t + r32) * 144 + (16 * d0 + 8 * hi) * 2);
;                 p[t] = __builtin_amdgcn_mfma_f32_32x32x16_bf16(kf, qr[d0], p[t], 0, 0, 0); }
;             if (t == 0) {
; #pragma unroll
;                 for (int i = 0; i < 16; ++i) { const int kc = (i & 3) + 8 * (i >> 2); p[t][i] = (kc >= lo) ? p[t][i] : -1e30f; }
;             }
	ds_read_b128 v[2:5], v125
	ds_read_b128 v[18:21], v125 offset:32
	v_cmp_gt_i32_e32 vcc, 1, v147
	s_waitcnt lgkmcnt(1)
	v_mfma_f32_32x32x16_bf16 v[2:17], v[2:5], v[48:51], 0
	s_waitcnt lgkmcnt(0)
	v_mfma_f32_32x32x16_bf16 v[2:17], v[18:21], v[80:83], v[2:17]
	ds_read_b128 v[18:21], v125 offset:64
	ds_read_b128 v[22:25], v125 offset:96
	s_waitcnt lgkmcnt(1)
	v_mfma_f32_32x32x16_bf16 v[2:17], v[18:21], v[84:87], v[2:17]
	s_waitcnt lgkmcnt(0)
	v_mfma_f32_32x32x16_bf16 v[2:17], v[22:25], v[88:91], v[2:17]
	s_nop 11
	v_cndmask_b32_e32 v102, v223, v2, vcc
	v_cmp_gt_i32_e32 vcc, 2, v147
	s_nop 1
	v_cndmask_b32_e32 v100, v223, v3, vcc
	v_cmp_gt_i32_e32 vcc, 3, v147
	s_nop 1
	v_cndmask_b32_e32 v99, v223, v4, vcc
	v_cmp_gt_i32_e32 vcc, 4, v147
	s_nop 1
	v_cndmask_b32_e32 v97, v223, v5, vcc
	v_cmp_gt_i32_e32 vcc, 9, v147
	s_nop 1
	v_cndmask_b32_e32 v92, v223, v6, vcc
	v_cmp_gt_i32_e32 vcc, 10, v147
	s_nop 1
	v_cndmask_b32_e32 v93, v223, v7, vcc
	v_cmp_gt_i32_e32 vcc, 11, v147
	s_nop 1
	v_cndmask_b32_e32 v94, v223, v8, vcc
	v_cmp_gt_i32_e32 vcc, 12, v147
	s_nop 1
	v_cndmask_b32_e32 v95, v223, v9, vcc
	v_cmp_gt_i32_e32 vcc, 17, v147
	s_nop 1
	v_cndmask_b32_e32 v96, v223, v10, vcc
	v_cmp_gt_i32_e32 vcc, 18, v147
	s_nop 1
	v_cndmask_b32_e32 v98, v223, v11, vcc
	v_cmp_gt_i32_e32 vcc, 19, v147
	s_nop 1
	v_cndmask_b32_e32 v101, v223, v12, vcc
	v_cmp_gt_i32_e32 vcc, 20, v147
	s_nop 1
	v_cndmask_b32_e32 v103, v223, v13, vcc
	v_cmp_gt_i32_e32 vcc, 25, v147
	s_nop 1
	v_cndmask_b32_e32 v108, v223, v14, vcc
	v_cmp_gt_i32_e32 vcc, 26, v147
	s_nop 1
	v_cndmask_b32_e32 v109, v223, v15, vcc
	v_cmp_gt_i32_e32 vcc, 27, v147
	s_nop 1
	v_cndmask_b32_e32 v110, v223, v16, vcc
	v_cmp_gt_i32_e32 vcc, 28, v147
	s_nop 1
	v_cndmask_b32_e32 v111, v223, v17, vcc

; #define LAS __attribute__((address_space(3)))
; __device__ __forceinline__ s16x4 vtr(const LAS unsigned char* p) { return __builtin_bit_cast(s16x4, __builtin_amdgcn_ds_read_tr16_b64_v4i16((LAS v4i16_t*)p)); }
; template <bool SAMPLE> ...
;     ...
;     u32x4 pw[5][2];
; #pragma unroll
;     for (int t = 0; t < 5; ++t) {
; #pragma unroll
;         for (int i = 0; i < 16; ++i) { p[t][i] = __builtin_amdgcn_exp2f(p[t][i] - mx); lsum += p[t][i]; }
; #pragma unroll
;         for (int s = 0; s < 2; ++s) { pw[t][s].x = pk_bf16(p[t][8 * s + 0], p[t][8 * s + 1]); pw[t][s].y = pk_bf16(p[t][8 * s + 2], p[t][8 * s + 3]); pw[t][s].z = pk_bf16(p[t][8 * s + 4], p[t][8 * s + 5]); pw[t][s].w = pk_bf16(p[t][8 * s + 6], p[t][8 * s + 7]); }
;     }
;     lsum += __shfl_xor(lsum, 32);
;     const float denom = lsum + __builtin_amdgcn_exp2f(sk - mx);
;     if (hi == 0) wsf[r32] = 1.0f / denom;
;     __builtin_amdgcn_sched_barrier(0);
;     f32x16 o[2];
; #pragma unroll
;     for (int d0 = 0; d0 < 2; ++d0)
; #pragma unroll
;         for (int i = 0; i < 16; ++i) o[d0][i] = 0.f;
;     const int i16 = lane & 15;
;     const LAS unsigned char* vb = Vl + (4 * hi + (i16 >> 2)) * 64 + ((lane >> 4) & 1) * 32 + (i16 & 3) * 8;
; #pragma unroll
;     for (int t = 0; t < 5; ++t)
; #pragma unroll
;         for (int s = 0; s < 2; ++s) {
;             const bf16x8 pa = __builtin_bit_cast(bf16x8, pw[t][s]);
; #pragma unroll
;             for (int d0 = 0; d0 < 2; ++d0) {
;                 const s16x4 vlo = vtr(vb + d0 * vhalf + (32 * t + 16 * s) * 64), vhi = vtr(vb + d0 * vhalf + (32 * t + 16 * s + 8) * 64);
;                 const bf16x8 vf = (bf16x8){vlo[0], vlo[1], vlo[2], vlo[3], vhi[0], vhi[1], vhi[2], vhi[3]};
;                 o[d0] = __builtin_amdgcn_mfma_f32_32x32x16_bf16(pa, vf, o[d0], 0, 0, 0);
;             }
;         }
;     __builtin_amdgcn_sched_barrier(0);
;     asm volatile("s_waitcnt lgkmcnt(0)" ::: "memory");
.LBB0_530:
	s_or_b64 exec, exec, s[0:1]
	s_lshl_b32 s0, s36, 3
	v_cvt_pk_bf16_f32 v32, v32, v32
	s_addk_i32 s0, 0x4000
	v_mov_b32_e32 v33, v32
	s_waitcnt lgkmcnt(0)
	v_mov_b32_e32 v34, v32
	v_mov_b32_e32 v35, v32
	v_cvt_pk_bf16_f32 v36, v36, v37
	v_cvt_pk_bf16_f32 v37, v38, v39
	v_mov_b32_e32 v38, v32
	v_mov_b32_e32 v39, v32
	v_cvt_pk_bf16_f32 v40, v8, v9
	v_cvt_pk_bf16_f32 v41, v10, v11
	v_cvt_pk_bf16_f32 v42, v12, v13
	v_cvt_pk_bf16_f32 v43, v14, v15
	v_cvt_pk_bf16_f32 v44, v0, v1
	v_cvt_pk_bf16_f32 v45, v2, v3
	v_cvt_pk_bf16_f32 v46, v4, v5
	v_cvt_pk_bf16_f32 v47, v6, v7
	v_cvt_pk_bf16_f32 v110, v24, v25
	v_cvt_pk_bf16_f32 v111, v26, v27
	v_cvt_pk_bf16_f32 v112, v28, v29
	v_cvt_pk_bf16_f32 v113, v30, v31
	v_cvt_pk_bf16_f32 v114, v16, v17
	v_cvt_pk_bf16_f32 v115, v18, v19
	v_cvt_pk_bf16_f32 v116, v20, v21
	v_cvt_pk_bf16_f32 v117, v22, v23
	v_cvt_pk_bf16_f32 v72, v72, v73
	v_cvt_pk_bf16_f32 v73, v74, v77
	v_cvt_pk_bf16_f32 v74, v78, v79
	v_cvt_pk_bf16_f32 v75, v101, v102
	v_cvt_pk_bf16_f32 v64, v64, v65
	v_cvt_pk_bf16_f32 v65, v66, v67
	v_cvt_pk_bf16_f32 v66, v68, v69
	v_cvt_pk_bf16_f32 v67, v70, v71
	v_cvt_pk_bf16_f32 v56, v56, v57
	v_cvt_pk_bf16_f32 v57, v58, v59
	v_cvt_pk_bf16_f32 v58, v60, v61
	v_cvt_pk_bf16_f32 v59, v62, v63
	v_cvt_pk_bf16_f32 v16, v48, v49
	v_cvt_pk_bf16_f32 v17, v50, v51
	v_cvt_pk_bf16_f32 v18, v52, v53
	v_cvt_pk_bf16_f32 v19, v54, v55
	v_lshrrev_b32_e32 v0, 2, v130
	v_and_or_b32 v0, v0, 3, v100
	v_readlane_b32 s1, v255, 29
	v_lshlrev_b32_e32 v1, 1, v108
	v_and_b32_e32 v1, 32, v1
	v_lshl_add_u32 v0, v0, 6, s1
	v_and_b32_e32 v2, 24, v109
	v_add3_u32 v52, v0, v1, v2
	ds_read_b64_tr_b16 v[0:1], v52 offset:46080
	ds_read_b64_tr_b16 v[2:3], v52 offset:46592
	ds_read_b64_tr_b16 v[20:21], v52 offset:56320
	ds_read_b64_tr_b16 v[22:23], v52 offset:56832
	s_waitcnt lgkmcnt(2)
	v_mfma_f32_32x32x16_bf16 v[0:15], v[16:19], v[0:3], 0
	ds_read_b64_tr_b16 v[48:49], v52 offset:47104
	ds_read_b64_tr_b16 v[50:51], v52 offset:47616
	s_waitcnt lgkmcnt(2)
	v_mfma_f32_32x32x16_bf16 v[16:31], v[16:19], v[20:23], 0
	ds_read_b64_tr_b16 v[236:237], v52 offset:57344
	ds_read_b64_tr_b16 v[238:239], v52 offset:57856
	s_waitcnt lgkmcnt(2)
	v_mfma_f32_32x32x16_bf16 v[0:15], v[56:59], v[48:51], v[0:15]
	ds_read_b64_tr_b16 v[48:49], v52 offset:48128
	ds_read_b64_tr_b16 v[50:51], v52 offset:48640
	s_waitcnt lgkmcnt(2)
	v_mfma_f32_32x32x16_bf16 v[16:31], v[56:59], v[236:239], v[16:31]
	ds_read_b64_tr_b16 v[236:237], v52 offset:58368
	ds_read_b64_tr_b16 v[238:239], v52 offset:58880
	s_waitcnt lgkmcnt(2)
	v_mfma_f32_32x32x16_bf16 v[0:15], v[64:67], v[48:51], v[0:15]
	ds_read_b64_tr_b16 v[48:49], v52 offset:49152
	ds_read_b64_tr_b16 v[50:51], v52 offset:49664
	s_waitcnt lgkmcnt(2)
	v_mfma_f32_32x32x16_bf16 v[16:31], v[64:67], v[236:239], v[16:31]
	ds_read_b64_tr_b16 v[236:237], v52 offset:59392
	ds_read_b64_tr_b16 v[238:239], v52 offset:59904
	s_waitcnt lgkmcnt(2)
	v_mfma_f32_32x32x16_bf16 v[0:15], v[72:75], v[48:51], v[0:15]
	ds_read_b64_tr_b16 v[48:49], v52 offset:50176
	ds_read_b64_tr_b16 v[50:51], v52 offset:50688
	s_waitcnt lgkmcnt(2)
	v_mfma_f32_32x32x16_bf16 v[16:31], v[72:75], v[236:239], v[16:31]
	ds_read_b64_tr_b16 v[236:237], v52 offset:60416
	ds_read_b64_tr_b16 v[238:239], v52 offset:60928
	s_waitcnt lgkmcnt(2)
	v_mfma_f32_32x32x16_bf16 v[0:15], v[114:117], v[48:51], v[0:15]
	ds_read_b64_tr_b16 v[48:49], v52 offset:51200
	ds_read_b64_tr_b16 v[50:51], v52 offset:51712
	s_waitcnt lgkmcnt(2)
	v_mfma_f32_32x32x16_bf16 v[16:31], v[114:117], v[236:239], v[16:31]
	ds_read_b64_tr_b16 v[236:237], v52 offset:61440
	ds_read_b64_tr_b16 v[238:239], v52 offset:61952
	s_waitcnt lgkmcnt(2)
	v_mfma_f32_32x32x16_bf16 v[0:15], v[110:113], v[48:51], v[0:15]
	ds_read_b64_tr_b16 v[48:49], v52 offset:52224
	ds_read_b64_tr_b16 v[50:51], v52 offset:52736
	s_waitcnt lgkmcnt(2)
	v_mfma_f32_32x32x16_bf16 v[16:31], v[110:113], v[236:239], v[16:31]
	ds_read_b64_tr_b16 v[236:237], v52 offset:62464
	ds_read_b64_tr_b16 v[238:239], v52 offset:62976
	s_waitcnt lgkmcnt(2)
	v_mfma_f32_32x32x16_bf16 v[0:15], v[44:47], v[48:51], v[0:15]
	ds_read_b64_tr_b16 v[48:49], v52 offset:53248
	ds_read_b64_tr_b16 v[50:51], v52 offset:53760
	s_waitcnt lgkmcnt(2)
	v_mfma_f32_32x32x16_bf16 v[16:31], v[44:47], v[236:239], v[16:31]
	ds_read_b64_tr_b16 v[236:237], v52 offset:63488
	ds_read_b64_tr_b16 v[238:239], v52 offset:64000
	s_waitcnt lgkmcnt(2)
	v_mfma_f32_32x32x16_bf16 v[0:15], v[40:43], v[48:51], v[0:15]
	ds_read_b64_tr_b16 v[48:49], v52 offset:54272
	ds_read_b64_tr_b16 v[50:51], v52 offset:54784
	s_waitcnt lgkmcnt(2)
	v_mfma_f32_32x32x16_bf16 v[16:31], v[40:43], v[236:239], v[16:31]
	ds_read_b64_tr_b16 v[236:237], v52 offset:64512
	ds_read_b64_tr_b16 v[238:239], v52 offset:65024
	s_waitcnt lgkmcnt(2)
	v_mfma_f32_32x32x16_bf16 v[0:15], v[36:39], v[48:51], v[0:15]
	ds_read_b64_tr_b16 v[48:49], v52 offset:55296
	ds_read_b64_tr_b16 v[50:51], v52 offset:55808
	s_waitcnt lgkmcnt(2)
	v_mfma_f32_32x32x16_bf16 v[16:31], v[36:39], v[236:239], v[16:31]
	v_add_u32_e32 v240, 0xb400, v52
	ds_read_b64_tr_b16 v[236:237], v240 offset:19456
	ds_read_b64_tr_b16 v[238:239], v240 offset:19968
	s_waitcnt lgkmcnt(2)
	v_mfma_f32_32x32x16_bf16 v[0:15], v[32:35], v[48:51], v[0:15]
	s_waitcnt lgkmcnt(0)
	v_mfma_f32_32x32x16_bf16 v[16:31], v[32:35], v[236:239], v[16:31]
	v_readlane_b32 s1, v255, 19
	s_waitcnt lgkmcnt(0)
	s_nop 1
	v_lshl_add_u32 v40, v100, 2, s1
	ds_read_b128 v[32:35], v40
	ds_read_b128 v[36:39], v40 offset:32
	v_readlane_b32 s1, v255, 20
	s_waitcnt lgkmcnt(1)
; #define LAS __attribute__((address_space(3)))
; __device__ __forceinline__ u32x4 pack8(const float (&f)[8]) { u32x4 w; w.x = pk_bf16(f[0], f[1]); w.y = pk_bf16(f[2], f[3]); w.z = pk_bf16(f[4], f[5]); w.w = pk_bf16(f[6], f[7]); return w; }
; __device__ __forceinline__ int crow(int r, int hi) { return (r & 3) + 8 * (r >> 2) + 4 * hi; }
; template <bool SAMPLE> ...
;     ...
; #pragma unroll
;     for (int i = 0; i < 16; ++i) {
;         const int qq = crow(i, hi);
;         const float rl = wsf[qq];
; #pragma unroll
;         for (int d0 = 0; d0 < 2; ++d0) ost[qq * 64 + d0 * 32 + r32] = (bf16_t)(pk_bf16(o[d0][i] * rl, 0.f) & 0xffffu);
;     }
;     asm volatile("s_waitcnt lgkmcnt(0)" ::: "memory");
; #pragma unroll
;     for (int it4 = 0; it4 < 4; ++it4) {
;         const int qq = it4 * 8 + (lane >> 3), ch = lane & 7;
;         const int orow = SAMPLE ? row0 + (qq & 7) : row0 + qq;
;         const int ohead = SAMPLE ? head0 + (qq >> 3) : head0;
;         const u32x4 ow = *(const LAS u32x4*)(ost + qq * 64 + ch * 8);
;         float of[8], zf[8], yv[8];
;         unpack8(ow, of); unpack8(zw[it4], zf);
; #pragma unroll
;         for (int k = 0; k < 8; ++k) yv[k] = of[k] * zf[k];
;         *(u32x4*)(Y + (size_t)orow * D + 512 + ohead * 64 + ch * 8) = pack8(yv);
	v_mul_f32_e32 v0, v0, v32
	v_lshl_add_u32 v41, v98, 1, s1
	v_lshl_add_u32 v42, v97, 9, v41
	v_cvt_pk_bf16_f32 v0, v0, s0
	ds_write_b16 v42, v0
	v_mul_f32_e32 v0, v16, v32
	v_cvt_pk_bf16_f32 v0, v0, s0
	ds_write_b16 v42, v0 offset:64
	v_mul_f32_e32 v0, v1, v33
	v_cvt_pk_bf16_f32 v0, v0, s0
	v_lshl_add_u32 v16, v100, 7, v41
	ds_write_b16 v16, v0 offset:128
	v_mul_f32_e32 v0, v17, v33
	v_cvt_pk_bf16_f32 v0, v0, s0
	ds_write_b16 v16, v0 offset:192
	v_mul_f32_e32 v0, v2, v34
	v_cvt_pk_bf16_f32 v0, v0, s0
	ds_write_b16 v16, v0 offset:256
	v_mul_f32_e32 v0, v18, v34
	v_cvt_pk_bf16_f32 v0, v0, s0
	ds_write_b16 v16, v0 offset:320
	v_mul_f32_e32 v0, v3, v35
	v_cvt_pk_bf16_f32 v0, v0, s0
	ds_write_b16 v16, v0 offset:384
	v_mul_f32_e32 v0, v19, v35
	v_cvt_pk_bf16_f32 v0, v0, s0
	ds_write_b16 v16, v0 offset:448
	s_waitcnt lgkmcnt(8)
	v_mul_f32_e32 v0, v4, v36
	v_cvt_pk_bf16_f32 v0, v0, s0
	ds_write_b16 v16, v0 offset:1024
	v_mul_f32_e32 v0, v20, v36
	v_cvt_pk_bf16_f32 v0, v0, s0
	ds_write_b16 v16, v0 offset:1088
	v_mul_f32_e32 v0, v5, v37
	v_cvt_pk_bf16_f32 v0, v0, s0
	ds_write_b16 v16, v0 offset:1152
	v_mul_f32_e32 v0, v21, v37
	v_cvt_pk_bf16_f32 v0, v0, s0
	ds_write_b16 v16, v0 offset:1216
	v_mul_f32_e32 v0, v6, v38
	v_cvt_pk_bf16_f32 v0, v0, s0
	ds_write_b16 v16, v0 offset:1280
	v_mul_f32_e32 v0, v22, v38
	v_cvt_pk_bf16_f32 v0, v0, s0
	ds_write_b16 v16, v0 offset:1344
	v_mul_f32_e32 v0, v7, v39
	v_cvt_pk_bf16_f32 v0, v0, s0
	ds_write_b16 v16, v0 offset:1408
	ds_read_b128 v[0:3], v40 offset:64
	v_mul_f32_e32 v4, v23, v39
	v_cvt_pk_bf16_f32 v4, v4, s0
	ds_write_b16 v16, v4 offset:1472
	ds_read_b128 v[4:7], v40 offset:96
	s_waitcnt lgkmcnt(2)
	v_mul_f32_e32 v8, v8, v0
	v_mul_f32_e32 v0, v24, v0
	v_cvt_pk_bf16_f32 v0, v0, s0
	ds_write_b16 v16, v0 offset:2112
	v_mul_f32_e32 v0, v9, v1
	v_cvt_pk_bf16_f32 v0, v0, s0
	ds_write_b16 v16, v0 offset:2176
	v_mul_f32_e32 v0, v25, v1
	v_cvt_pk_bf16_f32 v0, v0, s0
	ds_write_b16 v16, v0 offset:2240
	v_mul_f32_e32 v0, v10, v2
	v_cvt_pk_bf16_f32 v0, v0, s0
	ds_write_b16 v16, v0 offset:2304
	v_mul_f32_e32 v0, v26, v2
	v_cvt_pk_bf16_f32 v0, v0, s0
	ds_write_b16 v16, v0 offset:2368
	v_mul_f32_e32 v0, v11, v3
	v_cvt_pk_bf16_f32 v0, v0, s0
	ds_write_b16 v16, v0 offset:2432
	v_mul_f32_e32 v0, v27, v3
	v_cvt_pk_bf16_f32 v0, v0, s0
	ds_write_b16 v16, v0 offset:2496
	s_waitcnt lgkmcnt(7)
	v_mul_f32_e32 v0, v12, v4
	v_cvt_pk_bf16_f32 v0, v0, s0
	ds_write_b16 v16, v0 offset:3072
	v_mul_f32_e32 v0, v28, v4
	v_cvt_pk_bf16_f32 v0, v0, s0
	ds_write_b16 v16, v0 offset:3136
	v_mul_f32_e32 v0, v13, v5
	v_cvt_pk_bf16_f32 v0, v0, s0
	ds_write_b16 v16, v0 offset:3200
	v_mul_f32_e32 v0, v29, v5
	v_cvt_pk_bf16_f32 v0, v0, s0
	ds_write_b16 v16, v0 offset:3264
	v_mul_f32_e32 v0, v14, v6
	v_cvt_pk_bf16_f32 v0, v0, s0
	ds_write_b16 v16, v0 offset:3328
	v_mul_f32_e32 v0, v30, v6
	v_cvt_pk_bf16_f32 v0, v0, s0
	ds_write_b16 v16, v0 offset:3392
	v_mul_f32_e32 v0, v15, v7
	v_cvt_pk_bf16_f32 v0, v0, s0
	ds_write_b16 v16, v0 offset:3456
	v_mul_f32_e32 v0, v31, v7
	v_cvt_pk_bf16_f32 v8, v8, s0
	v_cvt_pk_bf16_f32 v0, v0, s0
	ds_write_b16 v16, v8 offset:2048
	ds_write_b16 v16, v0 offset:3520
	v_or_b32_e32 v0, s0, v106
	v_lshlrev_b32_e32 v1, 7, v106
	s_waitcnt lgkmcnt(0)
	v_add3_u32 v18, s1, v1, v96
	v_ashrrev_i32_e32 v1, 31, v0
	v_lshlrev_b64 v[4:5], 11, v[0:1]
	ds_read_b128 v[0:3], v18
	v_lshl_add_u64 v[4:5], s[78:79], 0, v[4:5]
	v_mov_b32_e32 v97, v173
	v_lshl_add_u64 v[8:9], v[4:5], 0, v[96:97]
	ds_read_b128 v[4:7], v18 offset:1024
	s_waitcnt lgkmcnt(1)
; #define LAS __attribute__((address_space(3)))
; __device__ __forceinline__ u32x4 pack8(const float (&f)[8]) { u32x4 w; w.x = pk_bf16(f[0], f[1]); w.y = pk_bf16(f[2], f[3]); w.z = pk_bf16(f[4], f[5]); w.w = pk_bf16(f[6], f[7]); return w; }
; template <bool SAMPLE> ...
;     ...
; #pragma unroll
;     for (int it4 = 0; it4 < 4; ++it4) {
;         const int qq = it4 * 8 + (lane >> 3), ch = lane & 7;
;         const int orow = SAMPLE ? row0 + (qq & 7) : row0 + qq;
;         const int ohead = SAMPLE ? head0 + (qq >> 3) : head0;
;         const u32x4 ow = *(const LAS u32x4*)(ost + qq * 64 + ch * 8);
;         float of[8], zf[8], yv[8];
;         unpack8(ow, of); unpack8(zw[it4], zf);
; #pragma unroll
;         for (int k = 0; k < 8; ++k) yv[k] = of[k] * zf[k];
;         *(u32x4*)(Y + (size_t)orow * D + 512 + ohead * 64 + ch * 8) = pack8(yv);
;     }
	v_lshlrev_b32_e32 v10, 16, v0
	v_and_b32_e32 v11, 0xffff0000, v0
	v_lshlrev_b32_e32 v12, 16, v92
	v_and_b32_e32 v13, 0xffff0000, v92
	v_pk_mul_f32 v[10:11], v[12:13], v[10:11]
	v_lshlrev_b32_e32 v0, 16, v1
	v_and_b32_e32 v1, 0xffff0000, v1
	v_lshlrev_b32_e32 v12, 16, v93
	v_and_b32_e32 v13, 0xffff0000, v93
	v_readlane_b32 s0, v255, 26
	v_pk_mul_f32 v[12:13], v[12:13], v[0:1]
	v_lshlrev_b32_e32 v0, 16, v2
	v_and_b32_e32 v1, 0xffff0000, v2
	v_lshlrev_b32_e32 v14, 16, v94
	v_and_b32_e32 v15, 0xffff0000, v94
	v_readlane_b32 s1, v255, 27
	v_pk_mul_f32 v[14:15], v[14:15], v[0:1]
	v_lshlrev_b32_e32 v0, 16, v3
	v_and_b32_e32 v1, 0xffff0000, v3
	v_lshlrev_b32_e32 v2, 16, v95
	v_and_b32_e32 v3, 0xffff0000, v95
	v_lshl_add_u64 v[8:9], s[0:1], 1, v[8:9]
	s_mov_b64 s[0:1], 0x1800400
	v_pk_mul_f32 v[16:17], v[2:3], v[0:1]
	v_cvt_pk_bf16_f32 v0, v10, v11
	v_lshl_add_u64 v[10:11], v[8:9], 0, s[0:1]
	s_mov_b32 s0, 0x1800000
	v_add_co_u32_e32 v8, vcc, s0, v8
	v_cvt_pk_bf16_f32 v1, v12, v13
	v_cvt_pk_bf16_f32 v2, v14, v15
	v_cvt_pk_bf16_f32 v3, v16, v17
	v_addc_co_u32_e32 v9, vcc, 0, v9, vcc
	global_store_dwordx4 v[8:9], v[0:3], off offset:1024
	v_lshlrev_b32_e32 v8, 16, v90
	v_and_b32_e32 v9, 0xffff0000, v90
	s_waitcnt lgkmcnt(0)
	v_lshlrev_b32_e32 v0, 16, v4
	v_and_b32_e32 v1, 0xffff0000, v4
	v_lshlrev_b32_e32 v2, 16, v88
	v_and_b32_e32 v3, 0xffff0000, v88
	v_pk_mul_f32 v[0:1], v[2:3], v[0:1]
	v_lshlrev_b32_e32 v2, 16, v5
	v_and_b32_e32 v3, 0xffff0000, v5
	v_lshlrev_b32_e32 v4, 16, v89
	v_and_b32_e32 v5, 0xffff0000, v89
	v_pk_mul_f32 v[2:3], v[4:5], v[2:3]
	v_lshlrev_b32_e32 v4, 16, v6
	v_and_b32_e32 v5, 0xffff0000, v6
	v_pk_mul_f32 v[8:9], v[8:9], v[4:5]
	v_lshlrev_b32_e32 v4, 16, v7
	v_and_b32_e32 v5, 0xffff0000, v7
	v_lshlrev_b32_e32 v6, 16, v91
	v_and_b32_e32 v7, 0xffff0000, v91
	v_pk_mul_f32 v[12:13], v[6:7], v[4:5]
	ds_read_b128 v[4:7], v18 offset:2048
	v_cvt_pk_bf16_f32 v0, v0, v1
	v_cvt_pk_bf16_f32 v1, v2, v3
	v_cvt_pk_bf16_f32 v2, v8, v9
	v_cvt_pk_bf16_f32 v3, v12, v13
	global_store_dwordx4 v[10:11], v[0:3], off offset:128
	ds_read_b128 v[0:3], v18 offset:3072
	s_waitcnt lgkmcnt(1)
	v_lshlrev_b32_e32 v8, 16, v4
	v_and_b32_e32 v9, 0xffff0000, v4
	v_lshlrev_b32_e32 v12, 16, v84
	v_and_b32_e32 v13, 0xffff0000, v84
	v_pk_mul_f32 v[8:9], v[12:13], v[8:9]
	v_lshlrev_b32_e32 v4, 16, v5
	v_and_b32_e32 v5, 0xffff0000, v5
	v_lshlrev_b32_e32 v12, 16, v85
	v_and_b32_e32 v13, 0xffff0000, v85
	v_pk_mul_f32 v[12:13], v[12:13], v[4:5]
	v_lshlrev_b32_e32 v4, 16, v6
	v_and_b32_e32 v5, 0xffff0000, v6
	v_lshlrev_b32_e32 v14, 16, v86
	v_and_b32_e32 v15, 0xffff0000, v86
	v_pk_mul_f32 v[14:15], v[14:15], v[4:5]
	v_lshlrev_b32_e32 v4, 16, v7
	v_and_b32_e32 v5, 0xffff0000, v7
	v_lshlrev_b32_e32 v6, 16, v87
	v_and_b32_e32 v7, 0xffff0000, v87
	v_pk_mul_f32 v[16:17], v[6:7], v[4:5]
	v_cvt_pk_bf16_f32 v4, v8, v9
	v_cvt_pk_bf16_f32 v5, v12, v13
	v_cvt_pk_bf16_f32 v6, v14, v15
	v_cvt_pk_bf16_f32 v7, v16, v17
	global_store_dwordx4 v[10:11], v[4:7], off offset:256
	v_lshlrev_b32_e32 v8, 16, v82
	v_and_b32_e32 v9, 0xffff0000, v82
	s_waitcnt lgkmcnt(0)
	v_lshlrev_b32_e32 v4, 16, v0
	v_and_b32_e32 v5, 0xffff0000, v0
	v_lshlrev_b32_e32 v6, 16, v80
	v_and_b32_e32 v7, 0xffff0000, v80
	v_pk_mul_f32 v[4:5], v[6:7], v[4:5]
	v_lshlrev_b32_e32 v0, 16, v1
	v_and_b32_e32 v1, 0xffff0000, v1
	v_lshlrev_b32_e32 v6, 16, v81
	v_and_b32_e32 v7, 0xffff0000, v81
	v_pk_mul_f32 v[6:7], v[6:7], v[0:1]
	v_lshlrev_b32_e32 v0, 16, v2
	v_and_b32_e32 v1, 0xffff0000, v2
	v_pk_mul_f32 v[8:9], v[8:9], v[0:1]
	v_lshlrev_b32_e32 v0, 16, v3
	v_and_b32_e32 v1, 0xffff0000, v3
	v_lshlrev_b32_e32 v2, 16, v83
	v_and_b32_e32 v3, 0xffff0000, v83
	v_pk_mul_f32 v[12:13], v[2:3], v[0:1]
	v_cvt_pk_bf16_f32 v0, v4, v5
	v_cvt_pk_bf16_f32 v1, v6, v7
	v_cvt_pk_bf16_f32 v2, v8, v9
	v_cvt_pk_bf16_f32 v3, v12, v13
	global_store_dwordx4 v[10:11], v[0:3], off offset:384
	s_waitcnt lgkmcnt(0)
